# stack: gemm setup after barrier, 16B write-through stores, wave-major norm rows, hoisted norm-tail loads, double-buffered K fragments in both attention loops, non-leaders poll the global release word
# speedup vs baseline: 1.0223x; 1.0223x over previous
; __device__ __forceinline__ unsigned xb_ld(unsigned* p)              { return __hip_atomic_load(p, __ATOMIC_RELAXED, __HIP_MEMORY_SCOPE_AGENT); }
; __device__ __forceinline__ unsigned xb_add(unsigned* p, unsigned v) { return __hip_atomic_fetch_add(p, v, __ATOMIC_RELAXED, __HIP_MEMORY_SCOPE_AGENT); }
; #define XB_SPIN(cond, bar) do { unsigned _sp = 0; while (cond) { __builtin_amdgcn_s_sleep(1); \
;     if ((++_sp & 255u) == 0u) { if (xb_ld(&(bar)[XB_TMO])) break; if (_sp > XB_SPIN_CAP) { atomicAdd(&(bar)[XB_TMO], 1u); break; } } } } while (0)
; __device__ __forceinline__ void xcd_barrier(const XcdBarrier& b) {
;     ...
;         const unsigned old = xb_add(&bar[XB_XSUB(b.x)], 1u);
;         const unsigned gen = old / nloc;
;         if (old + 1u == (gen + 1u) * nloc) {
;             __builtin_amdgcn_fence(__ATOMIC_RELEASE, "agent");
;             asm volatile("s_waitcnt vmcnt(0)" ::: "memory");
;             const unsigned og = xb_add(&bar[XB_TOP], 1u);
;             const unsigned tg = og / nx;
;             if (og + 1u == (tg + 1u) * nx) xb_add(&bar[XB_TOPGEN], 1u);
;             else XB_SPIN(xb_ld(&bar[XB_TOPGEN]) == tg, bar);
;             __builtin_amdgcn_fence(__ATOMIC_ACQUIRE, "agent");
;             xb_add(&bar[XB_XGEN(b.x)], 1u);
;             asm volatile("s_waitcnt vmcnt(0)" ::: "memory");
;         } else {
;             XB_SPIN(xb_ld(&bar[XB_XGEN(b.x)]) == gen, bar);
.LBB0_2172:
	s_or_b64 exec, exec, s[10:11]
	v_cvt_f32_u32_e32 v4, v2
	s_waitcnt vmcnt(0)
	v_readfirstlane_b32 s6, v3
	v_sub_u32_e32 v3, 0, v2
	v_rcp_iflag_f32_e32 v4, v4
	v_add_u32_e32 v5, s6, v1
	v_mul_f32_e32 v4, 0x4f7ffffe, v4
	v_cvt_u32_f32_e32 v4, v4
	v_mul_lo_u32 v1, v3, v4
	v_mul_hi_u32 v1, v4, v1
	v_add_u32_e32 v1, v4, v1
	v_mul_hi_u32 v1, v5, v1
	v_mul_lo_u32 v3, v1, v2
	v_sub_u32_e32 v3, v5, v3
	v_add_u32_e32 v4, 1, v1
	v_cmp_ge_u32_e32 vcc, v3, v2
	s_nop 1
	v_cndmask_b32_e32 v1, v1, v4, vcc
	v_sub_u32_e32 v4, v3, v2
	v_cndmask_b32_e32 v3, v3, v4, vcc
	v_add_u32_e32 v4, 1, v1
	v_cmp_ge_u32_e32 vcc, v3, v2
	v_add_u32_e32 v3, 1, v5
	s_nop 0
	v_cndmask_b32_e32 v1, v1, v4, vcc
	v_mul_lo_u32 v4, v2, v1
	v_add_u32_e32 v2, v4, v2
	v_cmp_ne_u32_e32 vcc, v3, v2
	s_and_saveexec_b64 s[6:7], vcc
	s_xor_b64 s[10:11], exec, s[6:7]
	s_cbranch_execz .LBB0_2186
	v_readlane_b32 s6, v252, 57
	v_readlane_b32 s7, v252, 58
	s_waitcnt lgkmcnt(0)
	s_nop 3
	global_load_dword v0, v179, s[6:7] sc1
	s_waitcnt vmcnt(0)
	v_cmp_eq_u32_e32 vcc, v0, v1
	s_and_saveexec_b64 s[38:39], vcc
	s_cbranch_execz .LBB0_2185
	s_mov_b32 s6, 1
	s_mov_b64 s[40:41], 0
	s_branch .LBB0_2176

; __device__ __forceinline__ unsigned xb_ld(unsigned* p)              { return __hip_atomic_load(p, __ATOMIC_RELAXED, __HIP_MEMORY_SCOPE_AGENT); }
; #define XB_SPIN(cond, bar) do { unsigned _sp = 0; while (cond) { __builtin_amdgcn_s_sleep(1); \
;     if ((++_sp & 255u) == 0u) { if (xb_ld(&(bar)[XB_TMO])) break; if (_sp > XB_SPIN_CAP) { atomicAdd(&(bar)[XB_TMO], 1u); break; } } } } while (0)
; __device__ __forceinline__ void xcd_barrier(const XcdBarrier& b) {
;     ...
;             XB_SPIN(xb_ld(&bar[XB_XGEN(b.x)]) == gen, bar);
.LBB0_2178:
	v_readlane_b32 s22, v252, 57
	v_readlane_b32 s23, v252, 58
	s_add_i32 s6, s6, 1
	s_mov_b64 s[46:47], -1
	s_nop 2
	global_load_dword v0, v179, s[22:23] sc1
	s_waitcnt vmcnt(0)
	v_cmp_ne_u32_e32 vcc, v0, v1
	s_orn2_b64 s[44:45], vcc, exec
	s_branch .LBB0_2175

; __device__ __forceinline__ unsigned xb_ld(unsigned* p)              { return __hip_atomic_load(p, __ATOMIC_RELAXED, __HIP_MEMORY_SCOPE_AGENT); }
; __device__ __forceinline__ unsigned xb_add(unsigned* p, unsigned v) { return __hip_atomic_fetch_add(p, v, __ATOMIC_RELAXED, __HIP_MEMORY_SCOPE_AGENT); }
; #define XB_SPIN(cond, bar) do { unsigned _sp = 0; while (cond) { __builtin_amdgcn_s_sleep(1); \
;     if ((++_sp & 255u) == 0u) { if (xb_ld(&(bar)[XB_TMO])) break; if (_sp > XB_SPIN_CAP) { atomicAdd(&(bar)[XB_TMO], 1u); break; } } } } while (0)
; __device__ __forceinline__ void xcd_barrier(const XcdBarrier& b) {
;     ...
;         const unsigned old = xb_add(&bar[XB_XSUB(b.x)], 1u);
;         const unsigned gen = old / nloc;
;         if (old + 1u == (gen + 1u) * nloc) {
;             __builtin_amdgcn_fence(__ATOMIC_RELEASE, "agent");
;             asm volatile("s_waitcnt vmcnt(0)" ::: "memory");
;             const unsigned og = xb_add(&bar[XB_TOP], 1u);
;             const unsigned tg = og / nx;
;             if (og + 1u == (tg + 1u) * nx) xb_add(&bar[XB_TOPGEN], 1u);
;             else XB_SPIN(xb_ld(&bar[XB_TOPGEN]) == tg, bar);
;             __builtin_amdgcn_fence(__ATOMIC_ACQUIRE, "agent");
;             xb_add(&bar[XB_XGEN(b.x)], 1u);
;             asm volatile("s_waitcnt vmcnt(0)" ::: "memory");
;         } else {
;             XB_SPIN(xb_ld(&bar[XB_XGEN(b.x)]) == gen, bar);
.LBB0_2522:
	s_or_b64 exec, exec, s[2:3]
	v_cvt_f32_u32_e32 v4, v2
	s_waitcnt vmcnt(0)
	v_readfirstlane_b32 s2, v3
	v_sub_u32_e32 v3, 0, v2
	v_rcp_iflag_f32_e32 v4, v4
	v_add_u32_e32 v5, s2, v1
	v_mul_f32_e32 v4, 0x4f7ffffe, v4
	v_cvt_u32_f32_e32 v4, v4
	v_mul_lo_u32 v1, v3, v4
	v_mul_hi_u32 v1, v4, v1
	v_add_u32_e32 v1, v4, v1
	v_mul_hi_u32 v1, v5, v1
	v_mul_lo_u32 v3, v1, v2
	v_sub_u32_e32 v3, v5, v3
	v_add_u32_e32 v4, 1, v1
	v_cmp_ge_u32_e32 vcc, v3, v2
	s_nop 1
	v_cndmask_b32_e32 v1, v1, v4, vcc
	v_sub_u32_e32 v4, v3, v2
	v_cndmask_b32_e32 v3, v3, v4, vcc
	v_add_u32_e32 v4, 1, v1
	v_cmp_ge_u32_e32 vcc, v3, v2
	v_add_u32_e32 v3, 1, v5
	s_nop 0
	v_cndmask_b32_e32 v1, v1, v4, vcc
	v_mul_lo_u32 v4, v2, v1
	v_add_u32_e32 v2, v4, v2
	v_cmp_ne_u32_e32 vcc, v3, v2
	s_and_saveexec_b64 s[2:3], vcc
	s_xor_b64 s[2:3], exec, s[2:3]
	s_cbranch_execz .LBB0_2536
	v_readlane_b32 s6, v252, 57
	v_readlane_b32 s7, v252, 58
	s_waitcnt lgkmcnt(0)
	s_nop 3
	global_load_dword v0, v179, s[6:7] sc1
	s_waitcnt vmcnt(0)
	v_cmp_eq_u32_e32 vcc, v0, v1
	s_and_saveexec_b64 s[38:39], vcc
	s_cbranch_execz .LBB0_2535
	s_mov_b32 s6, 1
	s_mov_b64 s[40:41], 0
	s_branch .LBB0_2526

; __device__ __forceinline__ void norm_phase(float* __restrict__ X, bf16_t* __restrict__ H, const float* __restrict__ modl, int shiftIdx, int scaleIdx, int nrows, const float* __restrict__ PART, const float* __restrict__ XLAT) {
;     ...
;         for (int i = 0; i < 8; ++i) ss += x[i][0] * x[i][0] + x[i][1] * x[i][1] + x[i][2] * x[i][2] + x[i][3] * x[i][3];
;         ss = wave_sum(ss);
;         const float r = rsqrtf(ss * (1.f / DM) + EPS);
;         const int v = row < NLAT ? (row >> 11) : 4;
;         const float* sh = modl + (size_t)v * MODW + shiftIdx * DM; const float* scl = modl + (size_t)v * MODW + scaleIdx * DM;
; #pragma unroll
;         for (int i = 0; i < 8; ++i) { const int c = (i * 64 + lane) * 4; const f32x4 s4 = *(const f32x4*)(sh + c), c4 = *(const f32x4*)(scl + c);
;             const f32x4 h = x[i] * r * (c4 + 1.f) + s4;
.LBB0_2654:
	s_or_b64 exec, exec, s[38:39]
	s_waitcnt vmcnt(0)
	v_mul_f32_e32 v33, v29, v29
	v_mul_f32_e32 v41, v25, v25
	v_fmac_f32_e32 v33, v28, v28
	v_fmac_f32_e32 v41, v24, v24
	v_fmac_f32_e32 v33, v30, v30
	v_fmac_f32_e32 v41, v26, v26
	v_fmac_f32_e32 v33, v31, v31
	v_fmac_f32_e32 v41, v27, v27
	v_add_f32_e32 v33, v33, v41
	v_mul_f32_e32 v41, v21, v21
	v_fmac_f32_e32 v41, v20, v20
	v_fmac_f32_e32 v41, v22, v22
	v_fmac_f32_e32 v41, v23, v23
	v_add_f32_e32 v33, v41, v33
	v_mul_f32_e32 v41, v17, v17
	v_pk_mul_f32 v[66:67], v[8:9], v[8:9]
	v_pk_mul_f32 v[68:69], v[12:13], v[12:13]
	v_fmac_f32_e32 v41, v16, v16
	v_pk_mul_f32 v[62:63], v[10:11], v[10:11]
	v_pk_mul_f32 v[64:65], v[14:15], v[14:15]
	v_mov_b32_e32 v70, v66
	v_mov_b32_e32 v71, v68
	v_mov_b32_e32 v68, v67
	v_fmac_f32_e32 v41, v18, v18
	v_pk_add_f32 v[66:67], v[70:71], v[68:69]
	v_mov_b32_e32 v68, v62
	v_mov_b32_e32 v69, v64
	v_fmac_f32_e32 v41, v19, v19
	v_pk_add_f32 v[66:67], v[68:69], v[66:67]
	v_mov_b32_e32 v64, v63
	v_add_f32_e32 v33, v41, v33
	v_pk_add_f32 v[62:63], v[64:65], v[66:67]
	v_pk_mul_f32 v[58:59], v[0:1], v[0:1]
	v_pk_mul_f32 v[60:61], v[4:5], v[4:5]
	v_add_f32_e32 v33, v63, v33
	v_pk_mul_f32 v[54:55], v[2:3], v[2:3]
	v_pk_mul_f32 v[56:57], v[6:7], v[6:7]
	v_add_f32_e32 v33, v62, v33
	v_mov_b32_e32 v62, v58
	v_mov_b32_e32 v63, v60
	v_mov_b32_e32 v60, v59
	v_pk_add_f32 v[58:59], v[62:63], v[60:61]
	v_mov_b32_e32 v60, v54
	v_mov_b32_e32 v61, v56
	v_pk_add_f32 v[58:59], v[60:61], v[58:59]
	v_mov_b32_e32 v56, v55
	v_pk_add_f32 v[54:55], v[56:57], v[58:59]
	v_readlane_b32 s6, v255, 59
	v_add_f32_e32 v33, v55, v33
	v_add_f32_e32 v33, v54, v33
	ds_bpermute_b32 v41, v35, v33
	v_readlane_b32 s7, v255, 60
	s_mov_b32 s4, 0x18add000
	v_mov_b32_e32 v43, v179
	v_mov_b32_e32 v45, v179
	s_waitcnt lgkmcnt(0)
	v_add_f32_e32 v33, v33, v41
	ds_bpermute_b32 v41, v104, v33
	v_mov_b32_e32 v47, v179
	v_mov_b32_e32 v49, v179
	v_mov_b32_e32 v51, v179
	v_mov_b32_e32 v53, v179
	s_waitcnt lgkmcnt(0)
	v_add_f32_e32 v33, v33, v41
	ds_bpermute_b32 v41, v105, v33
	s_waitcnt lgkmcnt(0)
	v_add_f32_e32 v33, v33, v41
	ds_bpermute_b32 v41, v106, v33
	s_waitcnt lgkmcnt(0)
	v_add_f32_e32 v33, v33, v41
	ds_bpermute_b32 v41, v107, v33
	s_waitcnt lgkmcnt(0)
	v_add_f32_e32 v33, v33, v41
	ds_bpermute_b32 v41, v108, v33
	s_waitcnt lgkmcnt(0)
	v_add_f32_e32 v33, v33, v41
	v_fmamk_f32 v33, v33, 0x3a000000, v177
	v_cmp_gt_f32_e32 vcc, s18, v33
	v_mul_f32_e32 v41, 0x4b800000, v33
	s_nop 0
	v_cndmask_b32_e32 v33, v33, v41, vcc
	v_rsq_f32_e32 v33, v33
	s_nop 0
	v_mul_f32_e32 v41, 0x45800000, v33
	v_cndmask_b32_e32 v54, v33, v41, vcc
	v_min_i32_e32 v33, 0x2000, v32
	v_ashrrev_i32_e32 v33, 11, v33
	v_mul_hi_i32_i24_e32 v57, 0x12000, v33
	v_mul_i32_i24_e32 v56, 0x12000, v33
	v_lshl_add_u64 v[56:57], s[6:7], 0, v[56:57]
	s_mov_b64 s[6:7], 0x6000
	v_lshl_add_u64 v[58:59], v[56:57], 0, s[6:7]
	s_mov_b64 s[6:7], 0x8000
	v_lshl_add_u64 v[56:57], v[56:57], 0, s[6:7]
	v_mov_b32_e32 v41, v179
	v_lshl_add_u64 v[122:123], v[58:59], 0, v[178:179]
	v_lshl_add_u64 v[124:125], v[56:57], 0, v[178:179]
	global_load_dwordx4 v[60:63], v[122:123], off
	global_load_dwordx4 v[64:67], v[124:125], off
	v_lshl_add_u64 v[122:123], v[58:59], 0, v[40:41]
	v_lshl_add_u64 v[124:125], v[56:57], 0, v[40:41]
	global_load_dwordx4 v[68:71], v[122:123], off
	global_load_dwordx4 v[72:75], v[124:125], off
	v_lshl_add_u64 v[122:123], v[58:59], 0, v[42:43]
	v_lshl_add_u64 v[124:125], v[56:57], 0, v[42:43]
	global_load_dwordx4 v[76:79], v[122:123], off
	global_load_dwordx4 v[80:83], v[124:125], off
	v_lshl_add_u64 v[122:123], v[58:59], 0, v[44:45]
	v_lshl_add_u64 v[124:125], v[56:57], 0, v[44:45]
	global_load_dwordx4 v[84:87], v[122:123], off
	global_load_dwordx4 v[88:91], v[124:125], off
	v_lshl_add_u64 v[122:123], v[58:59], 0, v[46:47]
	v_lshl_add_u64 v[124:125], v[56:57], 0, v[46:47]
	global_load_dwordx4 v[92:95], v[122:123], off
	global_load_dwordx4 v[96:99], v[124:125], off
	v_lshl_add_u64 v[122:123], v[58:59], 0, v[48:49]
	v_lshl_add_u64 v[124:125], v[56:57], 0, v[48:49]
	global_load_dwordx4 v[100:103], v[122:123], off
	global_load_dwordx4 v[110:113], v[124:125], off
	v_lshl_add_u64 v[122:123], v[58:59], 0, v[50:51]
	v_lshl_add_u64 v[124:125], v[56:57], 0, v[50:51]
	global_load_dwordx4 v[114:117], v[122:123], off
	global_load_dwordx4 v[118:121], v[124:125], off
	v_pk_mul_f32 v[28:29], v[28:29], v[54:55] op_sel_hi:[1,0]
	v_pk_mul_f32 v[30:31], v[30:31], v[54:55] op_sel_hi:[1,0]
	v_pk_mul_f32 v[24:25], v[24:25], v[54:55] op_sel_hi:[1,0]
	v_pk_mul_f32 v[26:27], v[26:27], v[54:55] op_sel_hi:[1,0]
	v_pk_mul_f32 v[20:21], v[20:21], v[54:55] op_sel_hi:[1,0]
	v_pk_mul_f32 v[22:23], v[22:23], v[54:55] op_sel_hi:[1,0]
	v_pk_mul_f32 v[16:17], v[16:17], v[54:55] op_sel_hi:[1,0]
	v_pk_mul_f32 v[18:19], v[18:19], v[54:55] op_sel_hi:[1,0]
	v_pk_mul_f32 v[12:13], v[12:13], v[54:55] op_sel_hi:[1,0]
	v_pk_mul_f32 v[14:15], v[14:15], v[54:55] op_sel_hi:[1,0]
	v_pk_mul_f32 v[8:9], v[8:9], v[54:55] op_sel_hi:[1,0]
	v_pk_mul_f32 v[10:11], v[10:11], v[54:55] op_sel_hi:[1,0]
	v_pk_mul_f32 v[4:5], v[4:5], v[54:55] op_sel_hi:[1,0]
	v_pk_mul_f32 v[6:7], v[6:7], v[54:55] op_sel_hi:[1,0]
	v_readlane_b32 s6, v255, 41
	v_readlane_b32 s7, v255, 42
	v_add_u32_e32 v32, s64, v32
	v_pk_mul_f32 v[0:1], v[0:1], v[54:55] op_sel_hi:[1,0]
	v_pk_mul_f32 v[2:3], v[2:3], v[54:55] op_sel_hi:[1,0]
	s_waitcnt vmcnt(0)
; __device__ __forceinline__ unsigned cvt_pk_bf16(float lo, float hi) { unsigned r; asm("v_cvt_pk_bf16_f32 %0, %1, %2" : "=v"(r) : "v"(lo), "v"(hi)); return r; }
; __device__ __forceinline__ void norm_phase(float* __restrict__ X, bf16_t* __restrict__ H, const float* __restrict__ modl, int shiftIdx, int scaleIdx, int nrows, const float* __restrict__ PART, const float* __restrict__ XLAT) {
;     ...
;         for (int i = 0; i < 8; ++i) { const int c = (i * 64 + lane) * 4; const f32x4 s4 = *(const f32x4*)(sh + c), c4 = *(const f32x4*)(scl + c);
;             const f32x4 h = x[i] * r * (c4 + 1.f) + s4;
;             u32x2 w; w.x = cvt_pk_bf16(h[0], h[1]); w.y = cvt_pk_bf16(h[2], h[3]);
;             *(u32x2*)(H + (size_t)row * DM + c) = w; }
	v_pk_add_f32 v[64:65], v[64:65], 1.0 op_sel_hi:[1,0]
	s_nop 0
	v_pk_fma_f32 v[28:29], v[64:65], v[28:29], v[60:61]
	v_pk_add_f32 v[66:67], v[66:67], 1.0 op_sel_hi:[1,0]
	v_cvt_pk_bf16_f32 v60, v28, v29
	v_lshl_add_u64 v[28:29], s[92:93], 0, v[36:37]
	v_pk_fma_f32 v[30:31], v[66:67], v[30:31], v[62:63]
	v_add_co_u32_e32 v28, vcc, s4, v28
	v_cvt_pk_bf16_f32 v61, v30, v31
	s_nop 0
	v_addc_co_u32_e32 v29, vcc, 0, v29, vcc
	global_store_dwordx2 v[28:29], v[60:61], off
	v_lshl_add_u64 v[122:123], v[58:59], 0, v[52:53]
	v_lshl_add_u64 v[124:125], v[56:57], 0, v[52:53]
	global_load_dwordx4 v[60:63], v[122:123], off
	global_load_dwordx4 v[64:67], v[124:125], off
	v_lshl_add_u64 v[36:37], v[36:37], 0, s[6:7]
	v_readlane_b32 s6, v255, 43
	s_movk_i32 s4, 0x23ff
	v_readlane_b32 s7, v255, 44
	v_cmp_lt_i32_e32 vcc, s4, v32
	s_or_b64 s[10:11], vcc, s[10:11]
	v_lshl_add_u64 v[38:39], v[38:39], 0, s[6:7]
	v_pk_add_f32 v[72:73], v[72:73], 1.0 op_sel_hi:[1,0]
	v_pk_add_f32 v[74:75], v[74:75], 1.0 op_sel_hi:[1,0]
	v_pk_fma_f32 v[24:25], v[72:73], v[24:25], v[68:69]
	v_pk_fma_f32 v[26:27], v[74:75], v[26:27], v[70:71]
	s_nop 0
	v_cvt_pk_bf16_f32 v24, v24, v25
	v_cvt_pk_bf16_f32 v25, v26, v27
	s_nop 0
	global_store_dwordx2 v[28:29], v[24:25], off offset:512
	v_pk_add_f32 v[80:81], v[80:81], 1.0 op_sel_hi:[1,0]
	v_pk_add_f32 v[82:83], v[82:83], 1.0 op_sel_hi:[1,0]
	v_pk_fma_f32 v[20:21], v[80:81], v[20:21], v[76:77]
	v_pk_fma_f32 v[22:23], v[82:83], v[22:23], v[78:79]
	s_nop 0
	v_cvt_pk_bf16_f32 v20, v20, v21
	v_cvt_pk_bf16_f32 v21, v22, v23
	s_nop 0
	global_store_dwordx2 v[28:29], v[20:21], off offset:1024
	v_pk_add_f32 v[88:89], v[88:89], 1.0 op_sel_hi:[1,0]
	v_pk_add_f32 v[90:91], v[90:91], 1.0 op_sel_hi:[1,0]
	v_pk_fma_f32 v[16:17], v[88:89], v[16:17], v[84:85]
	v_pk_fma_f32 v[18:19], v[90:91], v[18:19], v[86:87]
	s_nop 0
	v_cvt_pk_bf16_f32 v16, v16, v17
	v_cvt_pk_bf16_f32 v17, v18, v19
	s_nop 0
	global_store_dwordx2 v[28:29], v[16:17], off offset:1536
	v_pk_add_f32 v[96:97], v[96:97], 1.0 op_sel_hi:[1,0]
	v_pk_add_f32 v[98:99], v[98:99], 1.0 op_sel_hi:[1,0]
	v_pk_fma_f32 v[12:13], v[96:97], v[12:13], v[92:93]
	v_pk_fma_f32 v[14:15], v[98:99], v[14:15], v[94:95]
	s_nop 0
	v_cvt_pk_bf16_f32 v12, v12, v13
	v_cvt_pk_bf16_f32 v13, v14, v15
	s_nop 0
	global_store_dwordx2 v[28:29], v[12:13], off offset:2048
	v_pk_add_f32 v[110:111], v[110:111], 1.0 op_sel_hi:[1,0]
	v_pk_add_f32 v[112:113], v[112:113], 1.0 op_sel_hi:[1,0]
	v_pk_fma_f32 v[8:9], v[110:111], v[8:9], v[100:101]
	v_pk_fma_f32 v[10:11], v[112:113], v[10:11], v[102:103]
	s_nop 0
	v_cvt_pk_bf16_f32 v8, v8, v9
	v_cvt_pk_bf16_f32 v9, v10, v11
	s_nop 0
	global_store_dwordx2 v[28:29], v[8:9], off offset:2560
	v_pk_add_f32 v[118:119], v[118:119], 1.0 op_sel_hi:[1,0]
	v_pk_add_f32 v[120:121], v[120:121], 1.0 op_sel_hi:[1,0]
	v_pk_fma_f32 v[4:5], v[118:119], v[4:5], v[114:115]
	v_pk_fma_f32 v[6:7], v[120:121], v[6:7], v[116:117]
	s_nop 0
	v_cvt_pk_bf16_f32 v4, v4, v5
	v_cvt_pk_bf16_f32 v5, v6, v7
	s_nop 0
	global_store_dwordx2 v[28:29], v[4:5], off offset:3072
	s_waitcnt vmcnt(6)
	v_pk_add_f32 v[64:65], v[64:65], 1.0 op_sel_hi:[1,0]
	v_pk_add_f32 v[66:67], v[66:67], 1.0 op_sel_hi:[1,0]
	v_pk_fma_f32 v[0:1], v[64:65], v[0:1], v[60:61]
	v_pk_fma_f32 v[2:3], v[66:67], v[2:3], v[62:63]
	s_nop 0
	v_cvt_pk_bf16_f32 v0, v0, v1
	v_cvt_pk_bf16_f32 v1, v2, v3
	s_nop 0
	global_store_dwordx2 v[28:29], v[0:1], off offset:3584
	s_andn2_b64 exec, exec, s[10:11]
	s_cbranch_execz .LBB0_2657

; __device__ __forceinline__ unsigned xb_ld(unsigned* p)              { return __hip_atomic_load(p, __ATOMIC_RELAXED, __HIP_MEMORY_SCOPE_AGENT); }
; __device__ __forceinline__ unsigned xb_add(unsigned* p, unsigned v) { return __hip_atomic_fetch_add(p, v, __ATOMIC_RELAXED, __HIP_MEMORY_SCOPE_AGENT); }
; #define XB_SPIN(cond, bar) do { unsigned _sp = 0; while (cond) { __builtin_amdgcn_s_sleep(1); \
;     if ((++_sp & 255u) == 0u) { if (xb_ld(&(bar)[XB_TMO])) break; if (_sp > XB_SPIN_CAP) { atomicAdd(&(bar)[XB_TMO], 1u); break; } } } } while (0)
; __device__ __forceinline__ void xcd_barrier(const XcdBarrier& b) {
;     ...
;         const unsigned old = xb_add(&bar[XB_XSUB(b.x)], 1u);
;         const unsigned gen = old / nloc;
;         if (old + 1u == (gen + 1u) * nloc) {
;             __builtin_amdgcn_fence(__ATOMIC_RELEASE, "agent");
;             asm volatile("s_waitcnt vmcnt(0)" ::: "memory");
;             const unsigned og = xb_add(&bar[XB_TOP], 1u);
;             const unsigned tg = og / nx;
;             if (og + 1u == (tg + 1u) * nx) xb_add(&bar[XB_TOPGEN], 1u);
;             else XB_SPIN(xb_ld(&bar[XB_TOPGEN]) == tg, bar);
;             __builtin_amdgcn_fence(__ATOMIC_ACQUIRE, "agent");
;             xb_add(&bar[XB_XGEN(b.x)], 1u);
;             asm volatile("s_waitcnt vmcnt(0)" ::: "memory");
;         } else {
;             XB_SPIN(xb_ld(&bar[XB_XGEN(b.x)]) == gen, bar);
.LBB0_3228:
	s_or_b64 exec, exec, s[38:39]
	v_cvt_f32_u32_e32 v4, v2
	s_waitcnt vmcnt(0)
	v_readfirstlane_b32 s6, v3
	v_sub_u32_e32 v3, 0, v2
	v_rcp_iflag_f32_e32 v4, v4
	v_add_u32_e32 v5, s6, v1
	v_mul_f32_e32 v4, 0x4f7ffffe, v4
	v_cvt_u32_f32_e32 v4, v4
	v_mul_lo_u32 v1, v3, v4
	v_mul_hi_u32 v1, v4, v1
	v_add_u32_e32 v1, v4, v1
	v_mul_hi_u32 v1, v5, v1
	v_mul_lo_u32 v3, v1, v2
	v_sub_u32_e32 v3, v5, v3
	v_add_u32_e32 v4, 1, v1
	v_cmp_ge_u32_e32 vcc, v3, v2
	s_nop 1
	v_cndmask_b32_e32 v1, v1, v4, vcc
	v_sub_u32_e32 v4, v3, v2
	v_cndmask_b32_e32 v3, v3, v4, vcc
	v_add_u32_e32 v4, 1, v1
	v_cmp_ge_u32_e32 vcc, v3, v2
	v_add_u32_e32 v3, 1, v5
	s_nop 0
	v_cndmask_b32_e32 v1, v1, v4, vcc
	v_mul_lo_u32 v4, v2, v1
	v_add_u32_e32 v2, v4, v2
	v_cmp_ne_u32_e32 vcc, v3, v2
	s_and_saveexec_b64 s[6:7], vcc
	s_xor_b64 s[38:39], exec, s[6:7]
	s_cbranch_execz .LBB0_3242
	v_readlane_b32 s6, v252, 57
	v_readlane_b32 s7, v252, 58
	s_waitcnt lgkmcnt(0)
	s_nop 3
	global_load_dword v0, v179, s[6:7] sc1
	s_waitcnt vmcnt(0)
	v_cmp_eq_u32_e32 vcc, v0, v1
	s_and_saveexec_b64 s[40:41], vcc
	s_cbranch_execz .LBB0_3241
	s_mov_b32 s6, 1
	s_mov_b64 s[42:43], 0
	s_branch .LBB0_3232

; __device__ __forceinline__ unsigned xb_ld(unsigned* p)              { return __hip_atomic_load(p, __ATOMIC_RELAXED, __HIP_MEMORY_SCOPE_AGENT); }
; #define XB_SPIN(cond, bar) do { unsigned _sp = 0; while (cond) { __builtin_amdgcn_s_sleep(1); \
;     if ((++_sp & 255u) == 0u) { if (xb_ld(&(bar)[XB_TMO])) break; if (_sp > XB_SPIN_CAP) { atomicAdd(&(bar)[XB_TMO], 1u); break; } } } } while (0)
; __device__ __forceinline__ void xcd_barrier(const XcdBarrier& b) {
;     ...
;             XB_SPIN(xb_ld(&bar[XB_XGEN(b.x)]) == gen, bar);
.LBB0_3234:
	v_readlane_b32 s22, v252, 57
	v_readlane_b32 s23, v252, 58
	s_add_i32 s6, s6, 1
	s_mov_b64 s[48:49], -1
	s_nop 2
	global_load_dword v0, v179, s[22:23] sc1
	s_waitcnt vmcnt(0)
	v_cmp_ne_u32_e32 vcc, v0, v1
	s_orn2_b64 s[46:47], vcc, exec
	s_branch .LBB0_3231

; __device__ __forceinline__ void finishSM(f32x16& p0, f32x16& p1, float alpha, float& l_reg, bf16x8& pa0, bf16x8& pa1, bf16x8& pa2, bf16x8& pa3) {
; #pragma unroll
;     for (int r = 0; r < 16; ++r) p1[r] = __builtin_amdgcn_exp2f(p1[r]);
;     float ps = 0;
; #pragma unroll
;     for (int r = 0; r < 16; ++r) ps += p0[r];
; #pragma unroll
;     for (int r = 0; r < 16; ++r) ps += p1[r];
;     { auto rr = __builtin_amdgcn_permlane32_swap(__float_as_uint(ps), __float_as_uint(ps), false, false);
;       ps = __uint_as_float(rr[0]) + __uint_as_float(rr[1]); }
;     l_reg = l_reg * alpha + ps;
;     ...
;     PK4(p0, 0, pa0); PK4(p0, 8, pa1); PK4(p1, 0, pa2); PK4(p1, 8, pa3);
; template <int DQK> __device__ __forceinline__ void qkt(f32x16& p0, f32x16& p1, const char* Ks, const bf16x8* qr, int r32, int hi) {
;     p0 = f32x16{}; p1 = f32x16{};
; #pragma unroll
;     for (int d0 = 0; d0 < DQK / 16; ++d0) { const int cb = (d0 * 16 + hi * 8) * 2;
;         const bf16x8 b0 = *reinterpret_cast<const bf16x8*>(Ks + kswz<DQK>(r32, cb));
;         const bf16x8 b1 = *reinterpret_cast<const bf16x8*>(Ks + kswz<DQK>(32 + r32, cb));
;         p0 = __builtin_amdgcn_mfma_f32_32x32x16_bf16(b0, qr[d0], p0, 0, 0, 0);
;         p1 = __builtin_amdgcn_mfma_f32_32x32x16_bf16(b1, qr[d0], p1, 0, 0, 0); }
.LBB0_3449:
	s_mov_b32 s24, s25
	s_lshl_b32 s25, s7, 14
	s_add_i32 s14, s25, 0
	v_add_u32_e32 v68, s14, v169
	ds_read_b128 v[64:67], v68 offset:49152
	ds_read_b128 v[68:71], v68 offset:57344
	v_add_u32_e32 v158, s14, v171
	ds_read_b128 v[220:223], v158 offset:49152
	ds_read_b128 v[228:231], v158 offset:57344
	v_add_u32_e32 v158, s14, v170
	ds_read_b128 v[236:239], v158 offset:49152
	ds_read_b128 v[240:243], v158 offset:57344
	s_waitcnt lgkmcnt(4)
	v_mfma_f32_32x32x16_bf16 v[80:95], v[64:67], v[124:127], 0
	v_exp_f32_e32 v152, v152
	v_exp_f32_e32 v153, v153
	v_exp_f32_e32 v150, v150
	v_exp_f32_e32 v151, v151
	v_exp_f32_e32 v148, v148
	v_exp_f32_e32 v149, v149
	v_exp_f32_e32 v194, v147
	v_mfma_f32_32x32x16_bf16 v[64:79], v[68:71], v[124:127], 0
	v_exp_f32_e32 v195, v144
	v_exp_f32_e32 v227, v129
	v_cvt_pk_bf16_f32 v129, v207, v210
	v_cvt_pk_bf16_f32 v144, v196, v198
	v_cvt_pk_bf16_f32 v147, v150, v151
	s_waitcnt lgkmcnt(2)
	v_mfma_f32_32x32x16_bf16 v[80:95], v[220:223], v[120:123], v[80:95]
	v_mfma_f32_32x32x16_bf16 v[64:79], v[228:231], v[120:123], v[64:79]
	v_add_u32_e32 v158, s14, v168
	ds_read_b128 v[220:223], v158 offset:49152
	ds_read_b128 v[228:231], v158 offset:57344
	s_waitcnt lgkmcnt(2)
	v_mfma_f32_32x32x16_bf16 v[80:95], v[236:239], v[116:119], v[80:95]
	v_mfma_f32_32x32x16_bf16 v[64:79], v[240:243], v[116:119], v[64:79]
	v_add_u32_e32 v158, s14, v167
	ds_read_b128 v[236:239], v158 offset:49152
	ds_read_b128 v[240:243], v158 offset:57344
	s_waitcnt lgkmcnt(2)
	v_mfma_f32_32x32x16_bf16 v[80:95], v[220:223], v[112:115], v[80:95]
	v_mfma_f32_32x32x16_bf16 v[64:79], v[228:231], v[112:115], v[64:79]
	v_add_u32_e32 v158, s14, v163
	ds_read_b128 v[220:223], v158 offset:49152
	ds_read_b128 v[228:231], v158 offset:57344
	s_waitcnt lgkmcnt(2)
	v_mfma_f32_32x32x16_bf16 v[80:95], v[236:239], v[108:111], v[80:95]
	v_mfma_f32_32x32x16_bf16 v[64:79], v[240:243], v[108:111], v[64:79]
	v_add_u32_e32 v158, s14, v164
	ds_read_b128 v[236:239], v158 offset:49152
	ds_read_b128 v[240:243], v158 offset:57344
	s_waitcnt lgkmcnt(2)
	v_mfma_f32_32x32x16_bf16 v[80:95], v[220:223], v[104:107], v[80:95]
	v_mfma_f32_32x32x16_bf16 v[64:79], v[228:231], v[104:107], v[64:79]
	v_add_u32_e32 v158, s14, v165
	ds_read_b128 v[220:223], v158 offset:49152
	ds_read_b128 v[228:231], v158 offset:57344
	s_waitcnt lgkmcnt(2)
	v_mfma_f32_32x32x16_bf16 v[80:95], v[236:239], v[100:103], v[80:95]
	v_mfma_f32_32x32x16_bf16 v[64:79], v[240:243], v[100:103], v[64:79]
	v_exp_f32_e32 v158, v146
	v_cvt_pk_bf16_f32 v146, v152, v153
	s_waitcnt lgkmcnt(0)
	v_mfma_f32_32x32x16_bf16 v[80:95], v[220:223], v[96:99], v[80:95]
	v_exp_f32_e32 v223, v128
	v_add_f32_e32 v128, 0, v206
	v_add_f32_e32 v128, v209, v128
	v_add_f32_e32 v128, v207, v128
	v_add_f32_e32 v128, v210, v128
	v_add_f32_e32 v128, v208, v128
	v_add_f32_e32 v128, v211, v128
	v_add_f32_e32 v128, v204, v128
	v_add_f32_e32 v128, v205, v128
	v_add_f32_e32 v128, v200, v128
	v_add_f32_e32 v128, v202, v128
	v_add_f32_e32 v128, v201, v128
	v_add_f32_e32 v128, v203, v128
	v_add_f32_e32 v128, v196, v128
	v_add_f32_e32 v128, v198, v128
	v_add_f32_e32 v128, v197, v128
	v_add_f32_e32 v128, v199, v128
	v_add_f32_e32 v128, v152, v128
	v_add_f32_e32 v128, v153, v128
	v_add_f32_e32 v128, v150, v128
	v_add_f32_e32 v128, v151, v128
	v_add_f32_e32 v128, v148, v128
	v_exp_f32_e32 v220, v145
	v_add_f32_e32 v128, v149, v128
	v_exp_f32_e32 v221, v130
	v_add_f32_e32 v128, v158, v128
	v_exp_f32_e32 v222, v131
	v_add_f32_e32 v128, v194, v128
	v_add_f32_e32 v128, v195, v128
	v_add_f32_e32 v128, v220, v128
	v_mfma_f32_32x32x16_bf16 v[64:79], v[228:231], v[96:99], v[64:79]
	v_exp_f32_e32 v228, v142
	v_add_f32_e32 v128, v221, v128
	v_exp_f32_e32 v229, v143
	v_add_f32_e32 v128, v222, v128
	v_add_f32_e32 v128, v223, v128
	v_add_f32_e32 v128, v227, v128
	v_add_f32_e32 v128, v228, v128
	v_add_f32_e32 v174, v229, v128
	v_mov_b32_e32 v175, v174
	v_cvt_pk_bf16_f32 v128, v206, v209
	v_cvt_pk_bf16_f32 v130, v208, v211
	s_nop 1
	v_permlane32_swap_b32_e32 v174, v175
	v_cvt_pk_bf16_f32 v131, v204, v205
	v_permlane32_swap_b32_e32 v128, v130
	v_cvt_pk_bf16_f32 v142, v200, v202
	v_cvt_pk_bf16_f32 v143, v201, v203
	v_cvt_pk_bf16_f32 v145, v197, v199
	v_cvt_pk_bf16_f32 v148, v148, v149
	v_cvt_pk_bf16_f32 v149, v158, v194
	v_cvt_pk_bf16_f32 v150, v195, v220
	v_cvt_pk_bf16_f32 v151, v221, v222
	v_cvt_pk_bf16_f32 v152, v223, v227
	v_cvt_pk_bf16_f32 v153, v228, v229
	v_permlane32_swap_b32_e32 v129, v131
	v_permlane32_swap_b32_e32 v142, v144
	v_permlane32_swap_b32_e32 v143, v145
	v_permlane32_swap_b32_e32 v146, v148
	v_permlane32_swap_b32_e32 v147, v149
	v_permlane32_swap_b32_e32 v150, v152
	v_permlane32_swap_b32_e32 v151, v153
	s_lshl_b32 s26, s44, 14
	v_add_u32_e32 v158, s26, v159
	ds_read_b64_tr_b16 v[194:195], v158 offset:0
	ds_read_b64_tr_b16 v[196:197], v158 offset:0x800
	ds_read_b64_tr_b16 v[198:199], v158 offset:0x1000
	ds_read_b64_tr_b16 v[200:201], v158 offset:0x1800
	ds_read_b64_tr_b16 v[202:203], v158 offset:0x2000
	ds_read_b64_tr_b16 v[204:205], v158 offset:0x2800
	ds_read_b64_tr_b16 v[206:207], v158 offset:0x3000
	ds_read_b64_tr_b16 v[208:209], v158 offset:0x3800
	s_waitcnt lgkmcnt(0)
; #define SBAR() __builtin_amdgcn_sched_barrier(0)
; template <int D0> __device__ __forceinline__ void pv_one(f32x16& od, int vb, bf16x8 pa0, bf16x8 pa1, bf16x8 pa2, bf16x8 pa3) {
;     const s16x4 l0 = tr_read<v_rd_off(D0, 0, 0)>(vb), h0 = tr_read<v_rd_off(D0, 0, 1)>(vb), l1 = tr_read<v_rd_off(D0, 1, 0)>(vb), h1 = tr_read<v_rd_off(D0, 1, 1)>(vb);
;     const s16x4 l2 = tr_read<v_rd_off(D0, 2, 0)>(vb), h2 = tr_read<v_rd_off(D0, 2, 1)>(vb), l3 = tr_read<v_rd_off(D0, 3, 0)>(vb), h3 = tr_read<v_rd_off(D0, 3, 1)>(vb);
;     asm volatile("s_waitcnt lgkmcnt(0)" ::: "memory"); SBAR();
;     ...
;     od = __builtin_amdgcn_mfma_f32_32x32x16_bf16(pa0, PK(l0, h0), od, 0, 0, 0);
;     od = __builtin_amdgcn_mfma_f32_32x32x16_bf16(pa1, PK(l1, h1), od, 0, 0, 0);
;     od = __builtin_amdgcn_mfma_f32_32x32x16_bf16(pa2, PK(l2, h2), od, 0, 0, 0);
;     od = __builtin_amdgcn_mfma_f32_32x32x16_bf16(pa3, PK(l3, h3), od, 0, 0, 0);
;     ...
; }
; __device__ __forceinline__ void pv_d0(f32x16* o, int vb, bf16x8 pa0, bf16x8 pa1, bf16x8 pa2, bf16x8 pa3) {
;     pv_one<0>(o[0], vb, pa0, pa1, pa2, pa3); pv_one<1>(o[1], vb, pa0, pa1, pa2, pa3); pv_one<2>(o[2], vb, pa0, pa1, pa2, pa3); pv_one<3>(o[3], vb, pa0, pa1, pa2, pa3);
; }
; __device__ __forceinline__ void partialSM(f32x16& p0, f32x16& p1, float& m_reg, float& mn, float& alpha, const float C, const float thr_raw) {
;     float pmax = p0[0];
; #pragma unroll
;     for (int r = 1; r < 16; ++r) pmax = fmaxf(pmax, p0[r]);
; #pragma unroll
;     for (int r = 0; r < 16; ++r) pmax = fmaxf(pmax, p1[r]);
;     { auto rr = __builtin_amdgcn_permlane32_swap(__float_as_uint(pmax), __float_as_uint(pmax), false, false);
;       pmax = fmaxf(__uint_as_float(rr[0]), __uint_as_float(rr[1])); }
;     if (__builtin_expect(__all(pmax - m_reg <= thr_raw), 1)) { mn = m_reg; alpha = 1.f; }
; template <int LDQ, int LDK, int LDV> ...
;     ...
;     f32x16 pA0, pA1, pB0, pB1; float mnA, mnB, alA, alB; bf16x8 pa0, pa1, pa2, pa3; const int NT = seq / 64;
;     STAGE(0, 0); STAGE(1, 64); asm volatile("s_waitcnt vmcnt(0)" ::: "memory"); __syncthreads();
;     qkt<DQK>(pA0, pA1, K_lds, qr, r32, hi); partialSM(pA0, pA1, m_reg, mnA, alA, C, thr_raw);
;     STAGE(2, 128);
;     int bp = 0, bc = 1, bn = 2;
	s_nop 0
	v_mfma_f32_32x32x16_bf16 v[0:15], v[128:131], v[194:197], v[0:15]
	ds_read_b64_tr_b16 v[194:195], v158 offset:0x200
	ds_read_b64_tr_b16 v[196:197], v158 offset:0xa00
	v_mfma_f32_32x32x16_bf16 v[0:15], v[142:145], v[198:201], v[0:15]
	ds_read_b64_tr_b16 v[198:199], v158 offset:0x1200
	ds_read_b64_tr_b16 v[200:201], v158 offset:0x1a00
	v_mfma_f32_32x32x16_bf16 v[0:15], v[146:149], v[202:205], v[0:15]
	ds_read_b64_tr_b16 v[202:203], v158 offset:0x2200
	ds_read_b64_tr_b16 v[204:205], v158 offset:0x2a00
	v_mfma_f32_32x32x16_bf16 v[0:15], v[150:153], v[206:209], v[0:15]
	ds_read_b64_tr_b16 v[206:207], v158 offset:0x3200
	ds_read_b64_tr_b16 v[208:209], v158 offset:0x3a00
	s_waitcnt lgkmcnt(0)
	v_mfma_f32_32x32x16_bf16 v[48:63], v[128:131], v[194:197], v[48:63]
	ds_read_b64_tr_b16 v[194:195], v158 offset:0x400
	ds_read_b64_tr_b16 v[196:197], v158 offset:0xc00
	v_mfma_f32_32x32x16_bf16 v[48:63], v[142:145], v[198:201], v[48:63]
	ds_read_b64_tr_b16 v[198:199], v158 offset:0x1400
	ds_read_b64_tr_b16 v[200:201], v158 offset:0x1c00
	v_mfma_f32_32x32x16_bf16 v[48:63], v[146:149], v[202:205], v[48:63]
	ds_read_b64_tr_b16 v[202:203], v158 offset:0x2400
	ds_read_b64_tr_b16 v[204:205], v158 offset:0x2c00
	v_mfma_f32_32x32x16_bf16 v[48:63], v[150:153], v[206:209], v[48:63]
	ds_read_b64_tr_b16 v[206:207], v158 offset:0x3400
	ds_read_b64_tr_b16 v[208:209], v158 offset:0x3c00
	s_waitcnt lgkmcnt(0)
	v_mfma_f32_32x32x16_bf16 v[32:47], v[128:131], v[194:197], v[32:47]
	ds_read_b64_tr_b16 v[194:195], v158 offset:0x600
	ds_read_b64_tr_b16 v[196:197], v158 offset:0xe00
	v_mfma_f32_32x32x16_bf16 v[32:47], v[142:145], v[198:201], v[32:47]
	ds_read_b64_tr_b16 v[198:199], v158 offset:0x1600
	ds_read_b64_tr_b16 v[200:201], v158 offset:0x1e00
	v_mfma_f32_32x32x16_bf16 v[32:47], v[146:149], v[202:205], v[32:47]
	ds_read_b64_tr_b16 v[202:203], v158 offset:0x2600
	ds_read_b64_tr_b16 v[204:205], v158 offset:0x2e00
	v_mfma_f32_32x32x16_bf16 v[32:47], v[150:153], v[206:209], v[32:47]
	ds_read_b64_tr_b16 v[206:207], v158 offset:0x3600
	ds_read_b64_tr_b16 v[208:209], v158 offset:0x3e00
	s_waitcnt lgkmcnt(0)
	v_mfma_f32_32x32x16_bf16 v[16:31], v[128:131], v[194:197], v[16:31]
	v_max_f32_e32 v128, v81, v81
	v_max_f32_e32 v129, v80, v80
	v_max_f32_e32 v128, v129, v128
	v_max3_f32 v128, v128, v82, v83
	v_max3_f32 v128, v128, v84, v85
	v_max3_f32 v128, v128, v86, v87
	v_max3_f32 v128, v128, v88, v89
	v_mfma_f32_32x32x16_bf16 v[16:31], v[142:145], v[198:201], v[16:31]
	v_max3_f32 v128, v128, v90, v91
	v_max3_f32 v128, v128, v92, v93
	v_max3_f32 v128, v128, v94, v95
	v_max3_f32 v128, v128, v64, v65
	v_max3_f32 v128, v128, v66, v67
	v_max3_f32 v128, v128, v68, v69
	v_max3_f32 v128, v128, v70, v71
	v_mfma_f32_32x32x16_bf16 v[16:31], v[146:149], v[202:205], v[16:31]
	v_max3_f32 v128, v128, v72, v73
	v_max3_f32 v128, v128, v74, v75
	v_max3_f32 v128, v128, v76, v77
	v_max3_f32 v128, v128, v78, v79
	v_mov_b32_e32 v129, v128
	s_nop 1
	v_permlane32_swap_b32_e32 v128, v129
	v_mfma_f32_32x32x16_bf16 v[16:31], v[150:153], v[206:209], v[16:31]
	v_max_f32_e32 v129, v129, v129
	v_max_f32_e32 v128, v128, v128
	v_max_f32_e32 v128, v128, v129
	v_sub_f32_e32 v129, v128, v172
	v_cmp_ge_f32_e32 vcc, s20, v129
	s_cmp_eq_u64 vcc, exec
	s_waitcnt vmcnt(0)
	s_cselect_b64 s[40:41], -1, 0
	s_add_i32 s14, s22, -1
	v_cmp_lt_u32_e32 vcc, s14, v160
	s_waitcnt vmcnt(0)
	s_barrier
	s_and_saveexec_b64 s[42:43], vcc
	s_cbranch_execz .LBB0_3451
	s_sub_i32 s14, s23, 64
	v_cmp_lt_u32_e32 vcc, s14, v161
	s_nop 1
	v_cndmask_b32_e32 v129, v166, v162, vcc
	v_add_u32_e32 v130, s14, v129
	v_ashrrev_i32_e32 v131, 31, v130
	v_lshlrev_b64 v[130:131], 8, v[130:131]
	v_lshl_add_u64 v[142:143], s[86:87], 0, v[130:131]
	s_add_i32 s14, s6, s26
	v_lshl_add_u64 v[144:145], v[134:135], 1, v[142:143]
	s_mov_b32 m0, s14
	v_lshl_add_u64 v[142:143], v[136:137], 1, v[142:143]
	global_load_lds_dwordx4 v[144:145], off
	s_add_i32 m0, s14, 0x2000
	v_lshl_add_u64 v[130:131], s[84:85], 0, v[130:131]
	global_load_lds_dwordx4 v[142:143], off
	s_add_i32 m0, s14, 0xc000
	v_lshl_add_u64 v[142:143], v[138:139], 1, v[130:131]
	global_load_lds_dwordx4 v[142:143], off
	v_lshl_add_u64 v[130:131], v[140:141], 1, v[130:131]
	s_add_i32 m0, s14, 0xe000
	s_nop 0
	global_load_lds_dwordx4 v[130:131], off

; __device__ __forceinline__ void partialSM(f32x16& p0, f32x16& p1, float& m_reg, float& mn, float& alpha, const float C, const float thr_raw) {
;     ...
;     const float mnC = -mn * C;
; #pragma unroll
;     for (int r = 0; r < 16; ++r) p0[r] = fmaf(p0[r], C, mnC);
; #pragma unroll
;     for (int r = 0; r < 16; ++r) p1[r] = fmaf(p1[r], C, mnC);
; #pragma unroll
;     for (int r = 0; r < 16; ++r) p0[r] = __builtin_amdgcn_exp2f(p0[r]);
; }
; __device__ __forceinline__ void finishSM(f32x16& p0, f32x16& p1, float alpha, float& l_reg, bf16x8& pa0, bf16x8& pa1, bf16x8& pa2, bf16x8& pa3) {
; #pragma unroll
;     for (int r = 0; r < 16; ++r) p1[r] = __builtin_amdgcn_exp2f(p1[r]);
;     float ps = 0;
; #pragma unroll
;     for (int r = 0; r < 16; ++r) ps += p0[r];
; #pragma unroll
;     for (int r = 0; r < 16; ++r) ps += p1[r];
;     { auto rr = __builtin_amdgcn_permlane32_swap(__float_as_uint(ps), __float_as_uint(ps), false, false);
;       ps = __uint_as_float(rr[0]) + __uint_as_float(rr[1]); }
;     l_reg = l_reg * alpha + ps;
;     ...
;     PK4(p0, 0, pa0); PK4(p0, 8, pa1); PK4(p1, 0, pa2); PK4(p1, 8, pa3);
;     ...
; }
; template <int DQK> __device__ __forceinline__ void qkt(f32x16& p0, f32x16& p1, const char* Ks, const bf16x8* qr, int r32, int hi) {
;     p0 = f32x16{}; p1 = f32x16{};
; #pragma unroll
;     for (int d0 = 0; d0 < DQK / 16; ++d0) { const int cb = (d0 * 16 + hi * 8) * 2;
;         const bf16x8 b0 = *reinterpret_cast<const bf16x8*>(Ks + kswz<DQK>(r32, cb));
;         const bf16x8 b1 = *reinterpret_cast<const bf16x8*>(Ks + kswz<DQK>(32 + r32, cb));
;         p0 = __builtin_amdgcn_mfma_f32_32x32x16_bf16(b0, qr[d0], p0, 0, 0, 0);
;         p1 = __builtin_amdgcn_mfma_f32_32x32x16_bf16(b1, qr[d0], p1, 0, 0, 0); }
; }
.LBB0_3455:
	v_cndmask_b32_e64 v142, v128, v172, s[40:41]
	v_mul_f32_e32 v194, 0xbe0293ee, v142
	v_fmamk_f32 v80, v80, 0x3e0293ee, v194
	v_exp_f32_e32 v128, v80
	v_fmamk_f32 v81, v81, 0x3e0293ee, v194
	v_fmamk_f32 v82, v82, 0x3e0293ee, v194
	v_fmamk_f32 v83, v83, 0x3e0293ee, v194
	v_fmamk_f32 v84, v84, 0x3e0293ee, v194
	v_fmamk_f32 v85, v85, 0x3e0293ee, v194
	v_fmamk_f32 v86, v86, 0x3e0293ee, v194
	v_fmamk_f32 v87, v87, 0x3e0293ee, v194
	v_fmamk_f32 v88, v88, 0x3e0293ee, v194
	v_fmamk_f32 v89, v89, 0x3e0293ee, v194
	v_fmamk_f32 v90, v90, 0x3e0293ee, v194
	v_fmamk_f32 v91, v91, 0x3e0293ee, v194
	v_fmamk_f32 v92, v92, 0x3e0293ee, v194
	v_fmamk_f32 v93, v93, 0x3e0293ee, v194
	v_fmamk_f32 v94, v94, 0x3e0293ee, v194
	v_fmamk_f32 v95, v95, 0x3e0293ee, v194
	v_fmamk_f32 v204, v64, 0x3e0293ee, v194
	v_fmamk_f32 v205, v65, 0x3e0293ee, v194
	v_fmamk_f32 v206, v66, 0x3e0293ee, v194
	v_fmamk_f32 v207, v67, 0x3e0293ee, v194
	v_fmamk_f32 v208, v68, 0x3e0293ee, v194
	v_fmamk_f32 v197, v69, 0x3e0293ee, v194
	v_fmamk_f32 v198, v70, 0x3e0293ee, v194
	v_fmamk_f32 v199, v71, 0x3e0293ee, v194
	v_fmamk_f32 v200, v72, 0x3e0293ee, v194
	v_fmamk_f32 v201, v73, 0x3e0293ee, v194
	v_fmamk_f32 v202, v74, 0x3e0293ee, v194
	v_fmamk_f32 v203, v75, 0x3e0293ee, v194
	v_fmamk_f32 v196, v76, 0x3e0293ee, v194
	v_exp_f32_e32 v172, v81
	v_exp_f32_e32 v129, v82
	v_exp_f32_e32 v153, v83
	v_exp_f32_e32 v130, v84
	v_exp_f32_e32 v152, v85
	v_exp_f32_e32 v131, v86
	v_exp_f32_e32 v151, v87
	v_exp_f32_e32 v148, v88
	v_exp_f32_e32 v150, v89
	v_exp_f32_e32 v147, v90
	v_exp_f32_e32 v149, v91
	v_exp_f32_e32 v144, v92
	v_exp_f32_e32 v146, v93
	v_exp_f32_e32 v143, v94
	v_exp_f32_e32 v145, v95
	v_fmamk_f32 v209, v77, 0x3e0293ee, v194
	v_fmamk_f32 v210, v78, 0x3e0293ee, v194
	v_fmac_f32_e32 v194, 0x3e0293ee, v79
	s_lshl_b32 s27, s24, 14
	s_add_i32 s14, s27, 0
	v_add_u32_e32 v68, s14, v169
	ds_read_b128 v[64:67], v68 offset:49152
	ds_read_b128 v[68:71], v68 offset:57344
	v_add_u32_e32 v211, s14, v171
	ds_read_b128 v[220:223], v211 offset:49152
	ds_read_b128 v[228:231], v211 offset:57344
	v_add_u32_e32 v211, s14, v170
	ds_read_b128 v[236:239], v211 offset:49152
	ds_read_b128 v[240:243], v211 offset:57344
	s_waitcnt lgkmcnt(4)
	v_mfma_f32_32x32x16_bf16 v[80:95], v[64:67], v[124:127], 0
	v_exp_f32_e32 v204, v204
	v_exp_f32_e32 v205, v205
	v_exp_f32_e32 v206, v206
	v_exp_f32_e32 v207, v207
	v_exp_f32_e32 v208, v208
	v_exp_f32_e32 v197, v197
	v_exp_f32_e32 v198, v198
	v_mfma_f32_32x32x16_bf16 v[64:79], v[68:71], v[124:127], 0
	v_exp_f32_e32 v199, v199
	v_exp_f32_e32 v200, v200
	v_exp_f32_e32 v201, v201
	v_exp_f32_e32 v202, v202
	v_exp_f32_e32 v203, v203
	v_exp_f32_e32 v209, v209
	v_exp_f32_e32 v210, v210
	s_waitcnt lgkmcnt(2)
	v_mfma_f32_32x32x16_bf16 v[80:95], v[220:223], v[120:123], v[80:95]
	v_exp_f32_e32 v194, v194
	v_mfma_f32_32x32x16_bf16 v[64:79], v[228:231], v[120:123], v[64:79]
	v_add_u32_e32 v211, s14, v168
	ds_read_b128 v[220:223], v211 offset:49152
	ds_read_b128 v[228:231], v211 offset:57344
	s_waitcnt lgkmcnt(2)
	v_mfma_f32_32x32x16_bf16 v[80:95], v[236:239], v[116:119], v[80:95]
	v_mfma_f32_32x32x16_bf16 v[64:79], v[240:243], v[116:119], v[64:79]
	v_add_u32_e32 v211, s14, v167
	ds_read_b128 v[236:239], v211 offset:49152
	ds_read_b128 v[240:243], v211 offset:57344
	s_waitcnt lgkmcnt(2)
	v_mfma_f32_32x32x16_bf16 v[80:95], v[220:223], v[112:115], v[80:95]
	v_mfma_f32_32x32x16_bf16 v[64:79], v[228:231], v[112:115], v[64:79]
	v_add_u32_e32 v211, s14, v163
	ds_read_b128 v[220:223], v211 offset:49152
	ds_read_b128 v[228:231], v211 offset:57344
	s_waitcnt lgkmcnt(2)
	v_mfma_f32_32x32x16_bf16 v[80:95], v[236:239], v[108:111], v[80:95]
	v_mfma_f32_32x32x16_bf16 v[64:79], v[240:243], v[108:111], v[64:79]
	v_add_u32_e32 v211, s14, v164
	ds_read_b128 v[236:239], v211 offset:49152
	ds_read_b128 v[240:243], v211 offset:57344
	s_waitcnt lgkmcnt(2)
	v_mfma_f32_32x32x16_bf16 v[80:95], v[220:223], v[104:107], v[80:95]
	v_mfma_f32_32x32x16_bf16 v[64:79], v[228:231], v[104:107], v[64:79]
	v_add_u32_e32 v211, s14, v165
	ds_read_b128 v[220:223], v211 offset:49152
	ds_read_b128 v[228:231], v211 offset:57344
	s_waitcnt lgkmcnt(2)
	v_mfma_f32_32x32x16_bf16 v[80:95], v[236:239], v[100:103], v[80:95]
	v_mfma_f32_32x32x16_bf16 v[64:79], v[240:243], v[100:103], v[64:79]
	v_exp_f32_e32 v211, v196
	v_add_f32_e32 v196, 0, v128
	v_add_f32_e32 v196, v172, v196
	v_add_f32_e32 v196, v129, v196
	v_add_f32_e32 v196, v153, v196
	v_add_f32_e32 v196, v130, v196
	v_add_f32_e32 v196, v152, v196
	v_add_f32_e32 v196, v131, v196
	v_add_f32_e32 v196, v151, v196
	v_add_f32_e32 v196, v148, v196
	v_add_f32_e32 v196, v150, v196
	v_add_f32_e32 v196, v147, v196
	v_add_f32_e32 v196, v149, v196
	v_add_f32_e32 v196, v144, v196
	v_add_f32_e32 v196, v146, v196
	v_add_f32_e32 v196, v143, v196
	v_add_f32_e32 v196, v145, v196
	v_add_f32_e32 v196, v204, v196
	v_add_f32_e32 v196, v205, v196
	v_add_f32_e32 v196, v206, v196
	v_add_f32_e32 v196, v207, v196
	v_add_f32_e32 v196, v208, v196
	v_add_f32_e32 v196, v197, v196
	v_add_f32_e32 v196, v198, v196
	v_add_f32_e32 v196, v199, v196
	v_add_f32_e32 v196, v200, v196
	v_add_f32_e32 v196, v201, v196
	s_waitcnt lgkmcnt(0)
; template <int D0> __device__ __forceinline__ void pv_one(f32x16& od, int vb, bf16x8 pa0, bf16x8 pa1, bf16x8 pa2, bf16x8 pa3) {
;     const s16x4 l0 = tr_read<v_rd_off(D0, 0, 0)>(vb), h0 = tr_read<v_rd_off(D0, 0, 1)>(vb), l1 = tr_read<v_rd_off(D0, 1, 0)>(vb), h1 = tr_read<v_rd_off(D0, 1, 1)>(vb);
;     const s16x4 l2 = tr_read<v_rd_off(D0, 2, 0)>(vb), h2 = tr_read<v_rd_off(D0, 2, 1)>(vb), l3 = tr_read<v_rd_off(D0, 3, 0)>(vb), h3 = tr_read<v_rd_off(D0, 3, 1)>(vb);
;     asm volatile("s_waitcnt lgkmcnt(0)" ::: "memory"); SBAR();
;     ...
;     od = __builtin_amdgcn_mfma_f32_32x32x16_bf16(pa0, PK(l0, h0), od, 0, 0, 0);
;     od = __builtin_amdgcn_mfma_f32_32x32x16_bf16(pa1, PK(l1, h1), od, 0, 0, 0);
;     od = __builtin_amdgcn_mfma_f32_32x32x16_bf16(pa2, PK(l2, h2), od, 0, 0, 0);
;     od = __builtin_amdgcn_mfma_f32_32x32x16_bf16(pa3, PK(l3, h3), od, 0, 0, 0);
;     ...
; }
; __device__ __forceinline__ void pv_d0(f32x16* o, int vb, bf16x8 pa0, bf16x8 pa1, bf16x8 pa2, bf16x8 pa3) {
;     pv_one<0>(o[0], vb, pa0, pa1, pa2, pa3); pv_one<1>(o[1], vb, pa0, pa1, pa2, pa3); pv_one<2>(o[2], vb, pa0, pa1, pa2, pa3); pv_one<3>(o[3], vb, pa0, pa1, pa2, pa3);
; }
; __device__ __forceinline__ void partialSM(f32x16& p0, f32x16& p1, float& m_reg, float& mn, float& alpha, const float C, const float thr_raw) {
;     float pmax = p0[0];
; #pragma unroll
;     for (int r = 1; r < 16; ++r) pmax = fmaxf(pmax, p0[r]);
; #pragma unroll
;     for (int r = 0; r < 16; ++r) pmax = fmaxf(pmax, p1[r]);
;     { auto rr = __builtin_amdgcn_permlane32_swap(__float_as_uint(pmax), __float_as_uint(pmax), false, false);
;       pmax = fmaxf(__uint_as_float(rr[0]), __uint_as_float(rr[1])); }
;     if (__builtin_expect(__all(pmax - m_reg <= thr_raw), 1)) { mn = m_reg; alpha = 1.f; }
;     else { mn = fmaxf(m_reg, pmax); alpha = __builtin_amdgcn_exp2f((m_reg - mn) * C); m_reg = mn; }
;     const float mnC = -mn * C;
; #pragma unroll
;     for (int r = 0; r < 16; ++r) p0[r] = fmaf(p0[r], C, mnC);
; #pragma unroll
;     for (int r = 0; r < 16; ++r) p1[r] = fmaf(p1[r], C, mnC);
; #pragma unroll
;     for (int r = 0; r < 16; ++r) p0[r] = __builtin_amdgcn_exp2f(p0[r]);
; }
; __device__ __forceinline__ void finishSM(f32x16& p0, f32x16& p1, float alpha, float& l_reg, bf16x8& pa0, bf16x8& pa1, bf16x8& pa2, bf16x8& pa3) {
; #pragma unroll
;     for (int r = 0; r < 16; ++r) p1[r] = __builtin_amdgcn_exp2f(p1[r]);
	v_mfma_f32_32x32x16_bf16 v[80:95], v[220:223], v[96:99], v[80:95]
	v_add_f32_e32 v196, v202, v196
	v_add_f32_e32 v196, v203, v196
	v_add_f32_e32 v196, v211, v196
	v_add_f32_e32 v196, v209, v196
	v_add_f32_e32 v196, v210, v196
	v_add_f32_e32 v227, v194, v196
	v_cvt_pk_bf16_f32 v128, v128, v172
	v_mfma_f32_32x32x16_bf16 v[64:79], v[228:231], v[96:99], v[64:79]
	v_mov_b32_e32 v228, v227
	v_cvt_pk_bf16_f32 v130, v130, v152
	s_nop 1
	v_permlane32_swap_b32_e32 v227, v228
	v_cvt_pk_bf16_f32 v129, v129, v153
	v_cvt_pk_bf16_f32 v131, v131, v151
	v_permlane32_swap_b32_e32 v128, v130
	v_cvt_pk_bf16_f32 v148, v148, v150
	v_cvt_pk_bf16_f32 v149, v147, v149
	v_cvt_pk_bf16_f32 v150, v144, v146
	v_cvt_pk_bf16_f32 v151, v143, v145
	v_cvt_pk_bf16_f32 v144, v204, v205
	v_cvt_pk_bf16_f32 v145, v206, v207
	v_cvt_pk_bf16_f32 v146, v208, v197
	v_cvt_pk_bf16_f32 v147, v198, v199
	v_cvt_pk_bf16_f32 v196, v200, v201
	v_cvt_pk_bf16_f32 v197, v202, v203
	v_cvt_pk_bf16_f32 v198, v211, v209
	v_cvt_pk_bf16_f32 v199, v210, v194
	v_permlane32_swap_b32_e32 v129, v131
	v_permlane32_swap_b32_e32 v148, v150
	v_permlane32_swap_b32_e32 v149, v151
	v_permlane32_swap_b32_e32 v144, v146
	v_permlane32_swap_b32_e32 v145, v147
	v_permlane32_swap_b32_e32 v196, v198
	v_permlane32_swap_b32_e32 v197, v199
	v_add_u32_e32 v143, s25, v159
	ds_read_b64_tr_b16 v[200:201], v143 offset:0
	ds_read_b64_tr_b16 v[202:203], v143 offset:0x800
	ds_read_b64_tr_b16 v[204:205], v143 offset:0x1000
	ds_read_b64_tr_b16 v[206:207], v143 offset:0x1800
	ds_read_b64_tr_b16 v[208:209], v143 offset:0x2000
	ds_read_b64_tr_b16 v[210:211], v143 offset:0x2800
	ds_read_b64_tr_b16 v[220:221], v143 offset:0x3000
	ds_read_b64_tr_b16 v[222:223], v143 offset:0x3800
	s_waitcnt lgkmcnt(0)
	s_nop 0
	v_mfma_f32_32x32x16_bf16 v[0:15], v[128:131], v[200:203], v[0:15]
	ds_read_b64_tr_b16 v[200:201], v143 offset:0x200
	ds_read_b64_tr_b16 v[202:203], v143 offset:0xa00
	v_mfma_f32_32x32x16_bf16 v[0:15], v[148:151], v[204:207], v[0:15]
	ds_read_b64_tr_b16 v[204:205], v143 offset:0x1200
	ds_read_b64_tr_b16 v[206:207], v143 offset:0x1a00
	v_mfma_f32_32x32x16_bf16 v[0:15], v[144:147], v[208:211], v[0:15]
	ds_read_b64_tr_b16 v[208:209], v143 offset:0x2200
	ds_read_b64_tr_b16 v[210:211], v143 offset:0x2a00
	v_mfma_f32_32x32x16_bf16 v[0:15], v[196:199], v[220:223], v[0:15]
	ds_read_b64_tr_b16 v[220:221], v143 offset:0x3200
	ds_read_b64_tr_b16 v[222:223], v143 offset:0x3a00
	s_waitcnt lgkmcnt(0)
	v_mfma_f32_32x32x16_bf16 v[48:63], v[128:131], v[200:203], v[48:63]
	ds_read_b64_tr_b16 v[200:201], v143 offset:0x400
	ds_read_b64_tr_b16 v[202:203], v143 offset:0xc00
	v_mfma_f32_32x32x16_bf16 v[48:63], v[148:151], v[204:207], v[48:63]
	ds_read_b64_tr_b16 v[204:205], v143 offset:0x1400
	ds_read_b64_tr_b16 v[206:207], v143 offset:0x1c00
	v_mfma_f32_32x32x16_bf16 v[48:63], v[144:147], v[208:211], v[48:63]
	ds_read_b64_tr_b16 v[208:209], v143 offset:0x2400
	ds_read_b64_tr_b16 v[210:211], v143 offset:0x2c00
	v_mfma_f32_32x32x16_bf16 v[48:63], v[196:199], v[220:223], v[48:63]
	ds_read_b64_tr_b16 v[220:221], v143 offset:0x3400
	ds_read_b64_tr_b16 v[222:223], v143 offset:0x3c00
	s_waitcnt lgkmcnt(0)
	v_mfma_f32_32x32x16_bf16 v[32:47], v[128:131], v[200:203], v[32:47]
	ds_read_b64_tr_b16 v[200:201], v143 offset:0x600
	ds_read_b64_tr_b16 v[202:203], v143 offset:0xe00
	v_mfma_f32_32x32x16_bf16 v[32:47], v[148:151], v[204:207], v[32:47]
	ds_read_b64_tr_b16 v[204:205], v143 offset:0x1600
	ds_read_b64_tr_b16 v[206:207], v143 offset:0x1e00
	v_mfma_f32_32x32x16_bf16 v[32:47], v[144:147], v[208:211], v[32:47]
	ds_read_b64_tr_b16 v[208:209], v143 offset:0x2600
	ds_read_b64_tr_b16 v[210:211], v143 offset:0x2e00
	v_mfma_f32_32x32x16_bf16 v[32:47], v[196:199], v[220:223], v[32:47]
	ds_read_b64_tr_b16 v[220:221], v143 offset:0x3600
	ds_read_b64_tr_b16 v[222:223], v143 offset:0x3e00
	s_waitcnt lgkmcnt(0)
	v_mfma_f32_32x32x16_bf16 v[16:31], v[128:131], v[200:203], v[16:31]
	v_max_f32_e32 v128, v81, v81
	v_max_f32_e32 v129, v80, v80
	v_max_f32_e32 v128, v129, v128
	v_max3_f32 v128, v128, v82, v83
	v_max3_f32 v128, v128, v84, v85
	v_max3_f32 v128, v128, v86, v87
	v_max3_f32 v128, v128, v88, v89
	v_mfma_f32_32x32x16_bf16 v[16:31], v[148:151], v[204:207], v[16:31]
	v_max3_f32 v128, v128, v90, v91
	v_max3_f32 v128, v128, v92, v93
	v_max3_f32 v128, v128, v94, v95
	v_max3_f32 v128, v128, v64, v65
	v_max3_f32 v128, v128, v66, v67
	v_max3_f32 v128, v128, v68, v69
	v_max3_f32 v128, v128, v70, v71
	v_mfma_f32_32x32x16_bf16 v[16:31], v[144:147], v[208:211], v[16:31]
	v_max3_f32 v128, v128, v72, v73
	v_max3_f32 v128, v128, v74, v75
	v_max3_f32 v128, v128, v76, v77
	v_max3_f32 v128, v128, v78, v79
	v_mov_b32_e32 v129, v128
	s_nop 1
	v_permlane32_swap_b32_e32 v128, v129
	v_mfma_f32_32x32x16_bf16 v[16:31], v[196:199], v[220:223], v[16:31]
	v_max_f32_e32 v129, v129, v129
	v_max_f32_e32 v128, v128, v128
	v_max_f32_e32 v128, v128, v129
	v_sub_f32_e32 v129, v128, v142
	v_cmp_ge_f32_e32 vcc, s20, v129
	s_waitcnt vmcnt(0)
	s_cmp_eq_u64 vcc, exec
	s_cselect_b64 s[42:43], -1, 0
	v_cmp_lt_u32_e32 vcc, s22, v160
	v_cmp_ge_u32_e64 s[40:41], s22, v160
	s_waitcnt vmcnt(0)
	s_barrier
	s_and_saveexec_b64 s[48:49], vcc
	s_cbranch_execz .LBB0_3457
	v_cmp_lt_u32_e32 vcc, s23, v161
	s_add_i32 s14, s6, s25
	s_mov_b32 m0, s14
	v_cndmask_b32_e32 v129, v166, v162, vcc
	v_add_u32_e32 v130, s23, v129
	v_ashrrev_i32_e32 v131, 31, v130
	v_lshlrev_b64 v[130:131], 8, v[130:131]
	v_lshl_add_u64 v[144:145], s[86:87], 0, v[130:131]
	v_lshl_add_u64 v[146:147], v[134:135], 1, v[144:145]
	global_load_lds_dwordx4 v[146:147], off
	v_lshl_add_u64 v[144:145], v[136:137], 1, v[144:145]
	s_add_i32 m0, s14, 0x2000
	v_lshl_add_u64 v[130:131], s[84:85], 0, v[130:131]
	global_load_lds_dwordx4 v[144:145], off
	s_add_i32 m0, s14, 0xc000
	v_lshl_add_u64 v[144:145], v[138:139], 1, v[130:131]
	global_load_lds_dwordx4 v[144:145], off
	v_lshl_add_u64 v[130:131], v[140:141], 1, v[130:131]
	s_add_i32 m0, s14, 0xe000
	s_nop 0
	global_load_lds_dwordx4 v[130:131], off

; #define SBAR() __builtin_amdgcn_sched_barrier(0)
; template <int DQK> __device__ __forceinline__ void qkt(f32x16& p0, f32x16& p1, const char* Ks, const bf16x8* qr, int r32, int hi) {
;     p0 = f32x16{}; p1 = f32x16{};
; #pragma unroll
;     for (int d0 = 0; d0 < DQK / 16; ++d0) { const int cb = (d0 * 16 + hi * 8) * 2;
;         const bf16x8 b0 = *reinterpret_cast<const bf16x8*>(Ks + kswz<DQK>(r32, cb));
;         const bf16x8 b1 = *reinterpret_cast<const bf16x8*>(Ks + kswz<DQK>(32 + r32, cb));
;         p0 = __builtin_amdgcn_mfma_f32_32x32x16_bf16(b0, qr[d0], p0, 0, 0, 0);
;         p1 = __builtin_amdgcn_mfma_f32_32x32x16_bf16(b1, qr[d0], p1, 0, 0, 0); }
; }
; template <int DQK, int LDQ, int LDK, int LDV> ...
;     ...
;     const int NT = seq / 64;
;     STAGE(0, 0); asm volatile("s_waitcnt vmcnt(0)" ::: "memory"); __syncthreads();
;     for (int j = 0; j < NT; ++j) {
;         const int buf = j & 1;
;         if (j + 1 < NT) STAGE(buf ^ 1, (j + 1) * 64);
;         f32x16 p0, p1; float mn, al; bf16x8 pa0, pa1, pa2, pa3;
;         SBAR(); qkt<DQK>(p0, p1, K_lds + buf * SHM_K, qr, r32, hi);
;         partialSM(p0, p1, m_reg, mn, al, C, thr_raw);
;         if (__any(al < 1.f)) { if (hi == 0) al_l[r32] = al; asm volatile("s_waitcnt lgkmcnt(0)" ::: "memory");
.LBB0_3488:
	v_cmp_lt_u32_e32 vcc, s22, v169
	s_and_b32 s14, s7, 1
	s_lshl_b32 s23, s14, 14
	v_cndmask_b32_e32 v64, v203, v170, vcc
	v_add_u32_e32 v64, s22, v64
	v_ashrrev_i32_e32 v65, 31, v64
	v_lshlrev_b64 v[66:67], 11, v[64:65]
	v_lshl_add_u64 v[66:67], v[152:153], 0, v[66:67]
	s_xor_b32 s24, s23, 0x4000
	s_add_i32 s24, s6, s24
	v_lshl_add_u64 v[68:69], v[154:155], 1, v[66:67]
	v_lshl_add_u64 v[68:69], v[68:69], 0, s[36:37]
	s_mov_b32 m0, s24
	v_lshlrev_b64 v[64:65], 7, v[64:65]
	global_load_lds_dwordx4 v[68:69], off
	v_lshl_add_u64 v[68:69], v[156:157], 1, v[66:67]
	s_add_i32 m0, s24, 0x2000
	s_xor_b32 s24, s14, 1
	v_lshl_add_u64 v[68:69], v[68:69], 0, s[36:37]
	s_mulk_i32 s24, 0x6000
	v_lshl_add_u64 v[64:65], s[76:77], 0, v[64:65]
	global_load_lds_dwordx4 v[68:69], off
	s_add_i32 s24, s6, s24
	v_lshl_add_u64 v[68:69], v[178:179], 1, v[66:67]
	v_lshl_add_u64 v[70:71], v[158:159], 1, v[64:65]
	s_add_i32 m0, s24, 0x8000
	v_cndmask_b32_e64 v69, v69, v71, s[40:41]
	v_cndmask_b32_e64 v68, v68, v70, s[40:41]
	global_load_lds_dwordx4 v[68:69], off
	v_lshl_add_u64 v[68:69], v[148:149], 1, v[66:67]
	v_lshl_add_u64 v[70:71], v[160:161], 1, v[64:65]
	v_cndmask_b32_e64 v69, v69, v71, s[42:43]
	v_cndmask_b32_e64 v68, v68, v70, s[42:43]
	s_add_i32 m0, s24, 0xa000
	v_lshl_add_u64 v[66:67], v[150:151], 1, v[66:67]
	v_lshl_add_u64 v[64:65], v[162:163], 1, v[64:65]
	global_load_lds_dwordx4 v[68:69], off
	v_cndmask_b32_e64 v65, v67, v65, s[44:45]
	v_cndmask_b32_e64 v64, v66, v64, s[44:45]
	s_add_i32 m0, s24, 0xc000
	s_nop 0
	global_load_lds_dwordx4 v[64:65], off
	s_mulk_i32 s14, 0x6000
	s_add_i32 s14, s14, 0
	v_add_u32_e32 v174, s14, v171
	v_add_u32_e32 v64, v174, v202
	ds_read_b128 v[68:71], v64 offset:45056
	ds_read_b128 v[64:67], v64 offset:32768
	v_add_u32_e32 v210, v174, v201
	ds_read_b128 v[220:223], v210 offset:45056
	ds_read_b128 v[206:209], v210 offset:32768
	v_add_u32_e32 v210, v174, v200
	ds_read_b128 v[236:239], v210 offset:45056
	ds_read_b128 v[240:243], v210 offset:32768
	s_waitcnt lgkmcnt(4)
	v_mfma_f32_32x32x16_bf16 v[80:95], v[64:67], v[140:143], 0
	v_mfma_f32_32x32x16_bf16 v[64:79], v[68:71], v[140:143], 0
	s_waitcnt lgkmcnt(2)
	v_mfma_f32_32x32x16_bf16 v[80:95], v[206:209], v[136:139], v[80:95]
	v_mfma_f32_32x32x16_bf16 v[64:79], v[220:223], v[136:139], v[64:79]
	v_add_u32_e32 v210, v174, v199
	ds_read_b128 v[220:223], v210 offset:45056
	ds_read_b128 v[206:209], v210 offset:32768
	s_waitcnt lgkmcnt(2)
	v_mfma_f32_32x32x16_bf16 v[80:95], v[240:243], v[132:135], v[80:95]
	v_mfma_f32_32x32x16_bf16 v[64:79], v[236:239], v[132:135], v[64:79]
	v_add_u32_e32 v210, v174, v198
	ds_read_b128 v[236:239], v210 offset:45056
	ds_read_b128 v[240:243], v210 offset:32768
	s_waitcnt lgkmcnt(2)
	v_mfma_f32_32x32x16_bf16 v[80:95], v[206:209], v[128:131], v[80:95]
	v_mfma_f32_32x32x16_bf16 v[64:79], v[220:223], v[128:131], v[64:79]
	v_add_u32_e32 v210, v174, v197
	ds_read_b128 v[220:223], v210 offset:45056
	ds_read_b128 v[206:209], v210 offset:32768
	s_waitcnt lgkmcnt(2)
	v_mfma_f32_32x32x16_bf16 v[80:95], v[240:243], v[124:127], v[80:95]
	v_mfma_f32_32x32x16_bf16 v[64:79], v[236:239], v[124:127], v[64:79]
	v_add_u32_e32 v210, v174, v196
	ds_read_b128 v[236:239], v210 offset:45056
	ds_read_b128 v[240:243], v210 offset:32768
	s_waitcnt lgkmcnt(2)
	v_mfma_f32_32x32x16_bf16 v[80:95], v[206:209], v[120:123], v[80:95]
	v_mfma_f32_32x32x16_bf16 v[64:79], v[220:223], v[120:123], v[64:79]
	v_add_u32_e32 v210, v174, v195
	ds_read_b128 v[220:223], v210 offset:45056
	ds_read_b128 v[206:209], v210 offset:32768
	s_waitcnt lgkmcnt(2)
	v_mfma_f32_32x32x16_bf16 v[80:95], v[240:243], v[116:119], v[80:95]
	v_mfma_f32_32x32x16_bf16 v[64:79], v[236:239], v[116:119], v[64:79]
	v_add_u32_e32 v210, v174, v194
	ds_read_b128 v[236:239], v210 offset:45056
	ds_read_b128 v[240:243], v210 offset:32768
	s_waitcnt lgkmcnt(2)
	v_mfma_f32_32x32x16_bf16 v[80:95], v[206:209], v[112:115], v[80:95]
	v_mfma_f32_32x32x16_bf16 v[64:79], v[220:223], v[112:115], v[64:79]
	v_add_u32_e32 v210, v174, v175
	ds_read_b128 v[220:223], v210 offset:45056
	ds_read_b128 v[206:209], v210 offset:32768
	s_waitcnt lgkmcnt(2)
	v_mfma_f32_32x32x16_bf16 v[80:95], v[240:243], v[108:111], v[80:95]
	v_mfma_f32_32x32x16_bf16 v[64:79], v[236:239], v[108:111], v[64:79]
	v_add_u32_e32 v210, v174, v173
	ds_read_b128 v[236:239], v210 offset:45056
	ds_read_b128 v[240:243], v210 offset:32768
	s_waitcnt lgkmcnt(2)
	v_mfma_f32_32x32x16_bf16 v[80:95], v[206:209], v[104:107], v[80:95]
	v_mfma_f32_32x32x16_bf16 v[64:79], v[220:223], v[104:107], v[64:79]
	v_add_u32_e32 v210, v174, v172
	ds_read_b128 v[220:223], v210 offset:45056
	ds_read_b128 v[206:209], v210 offset:32768
	s_waitcnt lgkmcnt(2)
	v_mfma_f32_32x32x16_bf16 v[80:95], v[240:243], v[100:103], v[80:95]
	v_mfma_f32_32x32x16_bf16 v[64:79], v[236:239], v[100:103], v[64:79]
	s_waitcnt lgkmcnt(0)
	v_mfma_f32_32x32x16_bf16 v[80:95], v[206:209], v[96:99], v[80:95]
	v_mfma_f32_32x32x16_bf16 v[64:79], v[220:223], v[96:99], v[64:79]
	s_nop 10
	v_max_f32_e32 v174, v81, v81
	v_max_f32_e32 v206, v80, v80
	v_max_f32_e32 v174, v206, v174
	v_max3_f32 v174, v174, v82, v83
	v_max3_f32 v174, v174, v84, v85
	v_max3_f32 v174, v174, v86, v87
	v_max3_f32 v174, v174, v88, v89
	v_max3_f32 v174, v174, v90, v91
	v_max3_f32 v174, v174, v92, v93
	v_max3_f32 v174, v174, v94, v95
	v_max3_f32 v174, v174, v64, v65
	v_max3_f32 v174, v174, v66, v67
	v_max3_f32 v174, v174, v68, v69
	v_max3_f32 v174, v174, v70, v71
	v_max3_f32 v174, v174, v72, v73
	v_max3_f32 v174, v174, v74, v75
	v_max3_f32 v174, v174, v76, v77
	v_max3_f32 v174, v174, v78, v79
	v_mov_b32_e32 v206, v174
	s_nop 1
	v_permlane32_swap_b32_e32 v174, v206
	v_max_f32_e32 v206, v206, v206
	v_max_f32_e32 v174, v174, v174
	v_max_f32_e32 v174, v174, v206
	v_sub_f32_e32 v206, v174, v168
	v_cmp_ge_f32_e32 vcc, s21, v206
	v_max_f32_e32 v206, v168, v168
	v_max_f32_e32 v174, v206, v174
	v_sub_f32_e32 v206, v168, v174
	v_mul_f32_e32 v206, 0x3dd53b94, v206
	v_exp_f32_e32 v206, v206
	s_cmp_eq_u64 vcc, exec
	s_cselect_b64 s[46:47], -1, 0
	v_cndmask_b32_e64 v206, v206, 1.0, s[46:47]
	v_cmp_gt_f32_e32 vcc, 1.0, v206
	s_cbranch_vccz .LBB0_3487
	s_and_saveexec_b64 s[50:51], s[38:39]
	s_cbranch_execz .LBB0_3486
	ds_write_b32 v147, v206 offset:128
	s_branch .LBB0_3486

; __device__ __forceinline__ unsigned xb_ld(unsigned* p)              { return __hip_atomic_load(p, __ATOMIC_RELAXED, __HIP_MEMORY_SCOPE_AGENT); }
; __device__ __forceinline__ unsigned xb_add(unsigned* p, unsigned v) { return __hip_atomic_fetch_add(p, v, __ATOMIC_RELAXED, __HIP_MEMORY_SCOPE_AGENT); }
; #define XB_SPIN(cond, bar) do { unsigned _sp = 0; while (cond) { __builtin_amdgcn_s_sleep(1); \
;     if ((++_sp & 255u) == 0u) { if (xb_ld(&(bar)[XB_TMO])) break; if (_sp > XB_SPIN_CAP) { atomicAdd(&(bar)[XB_TMO], 1u); break; } } } } while (0)
; __device__ __forceinline__ void xcd_barrier(const XcdBarrier& b) {
;     ...
;         const unsigned old = xb_add(&bar[XB_XSUB(b.x)], 1u);
;         const unsigned gen = old / nloc;
;         if (old + 1u == (gen + 1u) * nloc) {
;             __builtin_amdgcn_fence(__ATOMIC_RELEASE, "agent");
;             asm volatile("s_waitcnt vmcnt(0)" ::: "memory");
;             const unsigned og = xb_add(&bar[XB_TOP], 1u);
;             const unsigned tg = og / nx;
;             if (og + 1u == (tg + 1u) * nx) xb_add(&bar[XB_TOPGEN], 1u);
;             else XB_SPIN(xb_ld(&bar[XB_TOPGEN]) == tg, bar);
;             __builtin_amdgcn_fence(__ATOMIC_ACQUIRE, "agent");
;             xb_add(&bar[XB_XGEN(b.x)], 1u);
;             asm volatile("s_waitcnt vmcnt(0)" ::: "memory");
;         } else {
;             XB_SPIN(xb_ld(&bar[XB_XGEN(b.x)]) == gen, bar);
.LBB0_3611:
	s_or_b64 exec, exec, s[38:39]
	v_cvt_f32_u32_e32 v4, v2
	s_waitcnt vmcnt(0)
	v_readfirstlane_b32 s4, v3
	v_sub_u32_e32 v3, 0, v2
	v_rcp_iflag_f32_e32 v4, v4
	v_add_u32_e32 v5, s4, v1
	v_mul_f32_e32 v4, 0x4f7ffffe, v4
	v_cvt_u32_f32_e32 v4, v4
	v_mul_lo_u32 v1, v3, v4
	v_mul_hi_u32 v1, v4, v1
	v_add_u32_e32 v1, v4, v1
	v_mul_hi_u32 v1, v5, v1
	v_mul_lo_u32 v3, v1, v2
	v_sub_u32_e32 v3, v5, v3
	v_add_u32_e32 v4, 1, v1
	v_cmp_ge_u32_e32 vcc, v3, v2
	s_nop 1
	v_cndmask_b32_e32 v1, v1, v4, vcc
	v_sub_u32_e32 v4, v3, v2
	v_cndmask_b32_e32 v3, v3, v4, vcc
	v_add_u32_e32 v4, 1, v1
	v_cmp_ge_u32_e32 vcc, v3, v2
	v_add_u32_e32 v3, 1, v5
	s_nop 0
	v_cndmask_b32_e32 v1, v1, v4, vcc
	v_mul_lo_u32 v4, v2, v1
	v_add_u32_e32 v2, v4, v2
	v_cmp_ne_u32_e32 vcc, v3, v2
	s_and_saveexec_b64 s[22:23], vcc
	s_xor_b64 s[38:39], exec, s[22:23]
	s_cbranch_execz .LBB0_3625
	v_readlane_b32 s22, v252, 57
	v_readlane_b32 s23, v252, 58
	s_waitcnt lgkmcnt(0)
	s_nop 3
	global_load_dword v0, v179, s[22:23] sc1
	s_waitcnt vmcnt(0)
	v_cmp_eq_u32_e32 vcc, v0, v1
	s_and_saveexec_b64 s[40:41], vcc
	s_cbranch_execz .LBB0_3624
	s_mov_b32 s4, 1
	s_mov_b64 s[42:43], 0
	s_branch .LBB0_3615

; __device__ __forceinline__ unsigned xb_ld(unsigned* p)              { return __hip_atomic_load(p, __ATOMIC_RELAXED, __HIP_MEMORY_SCOPE_AGENT); }
; #define XB_SPIN(cond, bar) do { unsigned _sp = 0; while (cond) { __builtin_amdgcn_s_sleep(1); \
;     if ((++_sp & 255u) == 0u) { if (xb_ld(&(bar)[XB_TMO])) break; if (_sp > XB_SPIN_CAP) { atomicAdd(&(bar)[XB_TMO], 1u); break; } } } } while (0)
; __device__ __forceinline__ void xcd_barrier(const XcdBarrier& b) {
;     ...
;             XB_SPIN(xb_ld(&bar[XB_XGEN(b.x)]) == gen, bar);
.LBB0_3617:
	v_readlane_b32 s22, v252, 57
	v_readlane_b32 s23, v252, 58
	s_add_i32 s4, s4, 1
	s_mov_b64 s[48:49], -1
	s_nop 2
	global_load_dword v0, v179, s[22:23] sc1
	s_waitcnt vmcnt(0)
	v_cmp_ne_u32_e32 vcc, v0, v1
	s_orn2_b64 s[46:47], vcc, exec
	s_branch .LBB0_3614

; __device__ __forceinline__ void norm_phase(float* __restrict__ X, bf16_t* __restrict__ H, const float* __restrict__ modl, int shiftIdx, int scaleIdx, int nrows, const float* __restrict__ PART, const float* __restrict__ XLAT) {
;     ...
;         for (int i = 0; i < 8; ++i) ss += x[i][0] * x[i][0] + x[i][1] * x[i][1] + x[i][2] * x[i][2] + x[i][3] * x[i][3];
;         ss = wave_sum(ss);
;         const float r = rsqrtf(ss * (1.f / DM) + EPS);
;         const int v = row < NLAT ? (row >> 11) : 4;
;         const float* sh = modl + (size_t)v * MODW + shiftIdx * DM; const float* scl = modl + (size_t)v * MODW + scaleIdx * DM;
; #pragma unroll
;         for (int i = 0; i < 8; ++i) { const int c = (i * 64 + lane) * 4; const f32x4 s4 = *(const f32x4*)(sh + c), c4 = *(const f32x4*)(scl + c);
;             const f32x4 h = x[i] * r * (c4 + 1.f) + s4;
.LBB0_3649:
	s_or_b64 exec, exec, s[44:45]
	s_waitcnt vmcnt(0)
	v_mul_f32_e32 v33, v29, v29
	v_mul_f32_e32 v41, v25, v25
	v_fmac_f32_e32 v33, v28, v28
	v_fmac_f32_e32 v41, v24, v24
	v_fmac_f32_e32 v33, v30, v30
	v_fmac_f32_e32 v41, v26, v26
	v_fmac_f32_e32 v33, v31, v31
	v_fmac_f32_e32 v41, v27, v27
	v_add_f32_e32 v33, v33, v41
	v_mul_f32_e32 v41, v21, v21
	v_fmac_f32_e32 v41, v20, v20
	v_fmac_f32_e32 v41, v22, v22
	v_fmac_f32_e32 v41, v23, v23
	v_add_f32_e32 v33, v41, v33
	v_mul_f32_e32 v41, v17, v17
	v_pk_mul_f32 v[66:67], v[8:9], v[8:9]
	v_pk_mul_f32 v[68:69], v[12:13], v[12:13]
	v_fmac_f32_e32 v41, v16, v16
	v_pk_mul_f32 v[62:63], v[10:11], v[10:11]
	v_pk_mul_f32 v[64:65], v[14:15], v[14:15]
	v_mov_b32_e32 v70, v66
	v_mov_b32_e32 v71, v68
	v_mov_b32_e32 v68, v67
	v_fmac_f32_e32 v41, v18, v18
	v_pk_add_f32 v[66:67], v[70:71], v[68:69]
	v_mov_b32_e32 v68, v62
	v_mov_b32_e32 v69, v64
	v_fmac_f32_e32 v41, v19, v19
	v_pk_add_f32 v[66:67], v[68:69], v[66:67]
	v_mov_b32_e32 v64, v63
	v_add_f32_e32 v33, v41, v33
	v_pk_add_f32 v[62:63], v[64:65], v[66:67]
	v_pk_mul_f32 v[58:59], v[0:1], v[0:1]
	v_pk_mul_f32 v[60:61], v[4:5], v[4:5]
	v_add_f32_e32 v33, v63, v33
	v_pk_mul_f32 v[54:55], v[2:3], v[2:3]
	v_pk_mul_f32 v[56:57], v[6:7], v[6:7]
	v_add_f32_e32 v33, v62, v33
	v_mov_b32_e32 v62, v58
	v_mov_b32_e32 v63, v60
	v_mov_b32_e32 v60, v59
	v_pk_add_f32 v[58:59], v[62:63], v[60:61]
	v_mov_b32_e32 v60, v54
	v_mov_b32_e32 v61, v56
	v_pk_add_f32 v[58:59], v[60:61], v[58:59]
	v_mov_b32_e32 v56, v55
	v_pk_add_f32 v[54:55], v[56:57], v[58:59]
	v_readlane_b32 s6, v255, 59
	v_add_f32_e32 v33, v55, v33
	v_add_f32_e32 v33, v54, v33
	ds_bpermute_b32 v41, v35, v33
	v_readlane_b32 s7, v255, 60
	v_mov_b32_e32 v43, v179
	v_mov_b32_e32 v45, v179
	v_mov_b32_e32 v47, v179
	s_waitcnt lgkmcnt(0)
	v_add_f32_e32 v33, v33, v41
	ds_bpermute_b32 v41, v104, v33
	v_mov_b32_e32 v49, v179
	v_mov_b32_e32 v51, v179
	v_mov_b32_e32 v53, v179
	s_waitcnt lgkmcnt(0)
	v_add_f32_e32 v33, v33, v41
	ds_bpermute_b32 v41, v105, v33
	s_waitcnt lgkmcnt(0)
	v_add_f32_e32 v33, v33, v41
	ds_bpermute_b32 v41, v106, v33
	s_waitcnt lgkmcnt(0)
	v_add_f32_e32 v33, v33, v41
	ds_bpermute_b32 v41, v107, v33
	s_waitcnt lgkmcnt(0)
	v_add_f32_e32 v33, v33, v41
	ds_bpermute_b32 v41, v108, v33
	s_waitcnt lgkmcnt(0)
	v_add_f32_e32 v33, v33, v41
	v_fmamk_f32 v33, v33, 0x3a000000, v177
	v_cmp_gt_f32_e32 vcc, s18, v33
	v_mul_f32_e32 v41, 0x4b800000, v33
	s_nop 0
	v_cndmask_b32_e32 v33, v33, v41, vcc
	v_rsq_f32_e32 v33, v33
	s_nop 0
	v_mul_f32_e32 v41, 0x45800000, v33
	v_cndmask_b32_e32 v54, v33, v41, vcc
	v_min_i32_e32 v33, 0x2000, v32
	v_ashrrev_i32_e32 v33, 11, v33
	v_mul_hi_i32_i24_e32 v57, 0x12000, v33
	v_mul_i32_i24_e32 v56, 0x12000, v33
	v_lshl_add_u64 v[56:57], s[6:7], 0, v[56:57]
	s_mov_b64 s[6:7], 0xc000
	v_lshl_add_u64 v[58:59], v[56:57], 0, s[6:7]
	s_mov_b64 s[6:7], 0xe000
	v_lshl_add_u64 v[56:57], v[56:57], 0, s[6:7]
	v_mov_b32_e32 v41, v179
	v_lshl_add_u64 v[122:123], v[58:59], 0, v[178:179]
	v_lshl_add_u64 v[124:125], v[56:57], 0, v[178:179]
	global_load_dwordx4 v[60:63], v[122:123], off
	global_load_dwordx4 v[64:67], v[124:125], off
	v_lshl_add_u64 v[122:123], v[58:59], 0, v[40:41]
	v_lshl_add_u64 v[124:125], v[56:57], 0, v[40:41]
	global_load_dwordx4 v[68:71], v[122:123], off
	global_load_dwordx4 v[72:75], v[124:125], off
	v_lshl_add_u64 v[122:123], v[58:59], 0, v[42:43]
	v_lshl_add_u64 v[124:125], v[56:57], 0, v[42:43]
	global_load_dwordx4 v[76:79], v[122:123], off
	global_load_dwordx4 v[80:83], v[124:125], off
	v_lshl_add_u64 v[122:123], v[58:59], 0, v[44:45]
	v_lshl_add_u64 v[124:125], v[56:57], 0, v[44:45]
	global_load_dwordx4 v[84:87], v[122:123], off
	global_load_dwordx4 v[88:91], v[124:125], off
	v_lshl_add_u64 v[122:123], v[58:59], 0, v[46:47]
	v_lshl_add_u64 v[124:125], v[56:57], 0, v[46:47]
	global_load_dwordx4 v[92:95], v[122:123], off
	global_load_dwordx4 v[96:99], v[124:125], off
	v_lshl_add_u64 v[122:123], v[58:59], 0, v[48:49]
	v_lshl_add_u64 v[124:125], v[56:57], 0, v[48:49]
	global_load_dwordx4 v[100:103], v[122:123], off
	global_load_dwordx4 v[110:113], v[124:125], off
	v_lshl_add_u64 v[122:123], v[58:59], 0, v[50:51]
	v_lshl_add_u64 v[124:125], v[56:57], 0, v[50:51]
	global_load_dwordx4 v[114:117], v[122:123], off
	global_load_dwordx4 v[118:121], v[124:125], off
	v_pk_mul_f32 v[28:29], v[28:29], v[54:55] op_sel_hi:[1,0]
	v_pk_mul_f32 v[30:31], v[30:31], v[54:55] op_sel_hi:[1,0]
	s_mov_b32 s6, 0x18add000
	v_pk_mul_f32 v[24:25], v[24:25], v[54:55] op_sel_hi:[1,0]
	v_pk_mul_f32 v[26:27], v[26:27], v[54:55] op_sel_hi:[1,0]
	v_pk_mul_f32 v[20:21], v[20:21], v[54:55] op_sel_hi:[1,0]
	v_pk_mul_f32 v[22:23], v[22:23], v[54:55] op_sel_hi:[1,0]
	v_pk_mul_f32 v[16:17], v[16:17], v[54:55] op_sel_hi:[1,0]
	v_pk_mul_f32 v[18:19], v[18:19], v[54:55] op_sel_hi:[1,0]
	v_pk_mul_f32 v[12:13], v[12:13], v[54:55] op_sel_hi:[1,0]
	v_pk_mul_f32 v[14:15], v[14:15], v[54:55] op_sel_hi:[1,0]
	v_pk_mul_f32 v[8:9], v[8:9], v[54:55] op_sel_hi:[1,0]
	v_pk_mul_f32 v[10:11], v[10:11], v[54:55] op_sel_hi:[1,0]
	v_pk_mul_f32 v[4:5], v[4:5], v[54:55] op_sel_hi:[1,0]
	v_pk_mul_f32 v[6:7], v[6:7], v[54:55] op_sel_hi:[1,0]
	v_add_u32_e32 v32, s64, v32
	v_pk_mul_f32 v[0:1], v[0:1], v[54:55] op_sel_hi:[1,0]
	v_pk_mul_f32 v[2:3], v[2:3], v[54:55] op_sel_hi:[1,0]
	s_waitcnt vmcnt(0)
; __device__ __forceinline__ unsigned cvt_pk_bf16(float lo, float hi) { unsigned r; asm("v_cvt_pk_bf16_f32 %0, %1, %2" : "=v"(r) : "v"(lo), "v"(hi)); return r; }
; __device__ __forceinline__ void norm_phase(float* __restrict__ X, bf16_t* __restrict__ H, const float* __restrict__ modl, int shiftIdx, int scaleIdx, int nrows, const float* __restrict__ PART, const float* __restrict__ XLAT) {
;     ...
;         for (int i = 0; i < 8; ++i) { const int c = (i * 64 + lane) * 4; const f32x4 s4 = *(const f32x4*)(sh + c), c4 = *(const f32x4*)(scl + c);
;             const f32x4 h = x[i] * r * (c4 + 1.f) + s4;
;             u32x2 w; w.x = cvt_pk_bf16(h[0], h[1]); w.y = cvt_pk_bf16(h[2], h[3]);
;             *(u32x2*)(H + (size_t)row * DM + c) = w; }
	v_pk_add_f32 v[64:65], v[64:65], 1.0 op_sel_hi:[1,0]
	s_nop 0
	v_pk_fma_f32 v[28:29], v[64:65], v[28:29], v[60:61]
	v_pk_add_f32 v[66:67], v[66:67], 1.0 op_sel_hi:[1,0]
	v_cvt_pk_bf16_f32 v60, v28, v29
	v_lshl_add_u64 v[28:29], s[92:93], 0, v[36:37]
	v_pk_fma_f32 v[30:31], v[66:67], v[30:31], v[62:63]
	v_add_co_u32_e32 v28, vcc, s6, v28
	v_cvt_pk_bf16_f32 v61, v30, v31
	s_nop 0
	v_addc_co_u32_e32 v29, vcc, 0, v29, vcc
	global_store_dwordx2 v[28:29], v[60:61], off
	v_lshl_add_u64 v[122:123], v[58:59], 0, v[52:53]
	v_lshl_add_u64 v[124:125], v[56:57], 0, v[52:53]
	global_load_dwordx4 v[60:63], v[122:123], off
	global_load_dwordx4 v[64:67], v[124:125], off
	v_readlane_b32 s6, v255, 41
	v_readlane_b32 s7, v255, 42
	v_cmp_le_i32_e32 vcc, s4, v32
	s_or_b64 s[42:43], vcc, s[42:43]
	v_lshl_add_u64 v[36:37], v[36:37], 0, s[6:7]
	v_readlane_b32 s6, v255, 43
	v_readlane_b32 s7, v255, 44
	v_lshl_add_u64 v[38:39], v[38:39], 0, s[6:7]
	v_pk_add_f32 v[72:73], v[72:73], 1.0 op_sel_hi:[1,0]
	v_pk_add_f32 v[74:75], v[74:75], 1.0 op_sel_hi:[1,0]
	v_pk_fma_f32 v[24:25], v[72:73], v[24:25], v[68:69]
	v_pk_fma_f32 v[26:27], v[74:75], v[26:27], v[70:71]
	s_nop 0
	v_cvt_pk_bf16_f32 v24, v24, v25
	v_cvt_pk_bf16_f32 v25, v26, v27
	s_nop 0
	global_store_dwordx2 v[28:29], v[24:25], off offset:512
	v_pk_add_f32 v[80:81], v[80:81], 1.0 op_sel_hi:[1,0]
	v_pk_add_f32 v[82:83], v[82:83], 1.0 op_sel_hi:[1,0]
	v_pk_fma_f32 v[20:21], v[80:81], v[20:21], v[76:77]
	v_pk_fma_f32 v[22:23], v[82:83], v[22:23], v[78:79]
	s_nop 0
	v_cvt_pk_bf16_f32 v20, v20, v21
	v_cvt_pk_bf16_f32 v21, v22, v23
	s_nop 0
	global_store_dwordx2 v[28:29], v[20:21], off offset:1024
	v_pk_add_f32 v[88:89], v[88:89], 1.0 op_sel_hi:[1,0]
	v_pk_add_f32 v[90:91], v[90:91], 1.0 op_sel_hi:[1,0]
	v_pk_fma_f32 v[16:17], v[88:89], v[16:17], v[84:85]
	v_pk_fma_f32 v[18:19], v[90:91], v[18:19], v[86:87]
	s_nop 0
	v_cvt_pk_bf16_f32 v16, v16, v17
	v_cvt_pk_bf16_f32 v17, v18, v19
	s_nop 0
	global_store_dwordx2 v[28:29], v[16:17], off offset:1536
	v_pk_add_f32 v[96:97], v[96:97], 1.0 op_sel_hi:[1,0]
	v_pk_add_f32 v[98:99], v[98:99], 1.0 op_sel_hi:[1,0]
	v_pk_fma_f32 v[12:13], v[96:97], v[12:13], v[92:93]
	v_pk_fma_f32 v[14:15], v[98:99], v[14:15], v[94:95]
	s_nop 0
	v_cvt_pk_bf16_f32 v12, v12, v13
	v_cvt_pk_bf16_f32 v13, v14, v15
	s_nop 0
	global_store_dwordx2 v[28:29], v[12:13], off offset:2048
	v_pk_add_f32 v[110:111], v[110:111], 1.0 op_sel_hi:[1,0]
	v_pk_add_f32 v[112:113], v[112:113], 1.0 op_sel_hi:[1,0]
	v_pk_fma_f32 v[8:9], v[110:111], v[8:9], v[100:101]
	v_pk_fma_f32 v[10:11], v[112:113], v[10:11], v[102:103]
	s_nop 0
	v_cvt_pk_bf16_f32 v8, v8, v9
	v_cvt_pk_bf16_f32 v9, v10, v11
	s_nop 0
	global_store_dwordx2 v[28:29], v[8:9], off offset:2560
	v_pk_add_f32 v[118:119], v[118:119], 1.0 op_sel_hi:[1,0]
	v_pk_add_f32 v[120:121], v[120:121], 1.0 op_sel_hi:[1,0]
	v_pk_fma_f32 v[4:5], v[118:119], v[4:5], v[114:115]
	v_pk_fma_f32 v[6:7], v[120:121], v[6:7], v[116:117]
	s_nop 0
	v_cvt_pk_bf16_f32 v4, v4, v5
	v_cvt_pk_bf16_f32 v5, v6, v7
	s_nop 0
	global_store_dwordx2 v[28:29], v[4:5], off offset:3072
	s_waitcnt vmcnt(6)
	v_pk_add_f32 v[64:65], v[64:65], 1.0 op_sel_hi:[1,0]
	v_pk_add_f32 v[66:67], v[66:67], 1.0 op_sel_hi:[1,0]
	v_pk_fma_f32 v[0:1], v[64:65], v[0:1], v[60:61]
	v_pk_fma_f32 v[2:3], v[66:67], v[2:3], v[62:63]
	s_nop 0
	v_cvt_pk_bf16_f32 v0, v0, v1
	v_cvt_pk_bf16_f32 v1, v2, v3
	s_nop 0
	global_store_dwordx2 v[28:29], v[0:1], off offset:3584
	s_andn2_b64 exec, exec, s[42:43]
	s_cbranch_execz .LBB0_3652

; __device__ __forceinline__ unsigned xb_ld(unsigned* p)              { return __hip_atomic_load(p, __ATOMIC_RELAXED, __HIP_MEMORY_SCOPE_AGENT); }
; __device__ __forceinline__ unsigned xb_add(unsigned* p, unsigned v) { return __hip_atomic_fetch_add(p, v, __ATOMIC_RELAXED, __HIP_MEMORY_SCOPE_AGENT); }
; #define XB_SPIN(cond, bar) do { unsigned _sp = 0; while (cond) { __builtin_amdgcn_s_sleep(1); \
;     if ((++_sp & 255u) == 0u) { if (xb_ld(&(bar)[XB_TMO])) break; if (_sp > XB_SPIN_CAP) { atomicAdd(&(bar)[XB_TMO], 1u); break; } } } } while (0)
; __device__ __forceinline__ void xcd_barrier(const XcdBarrier& b) {
;     ...
;         const unsigned old = xb_add(&bar[XB_XSUB(b.x)], 1u);
;         const unsigned gen = old / nloc;
;         if (old + 1u == (gen + 1u) * nloc) {
;             __builtin_amdgcn_fence(__ATOMIC_RELEASE, "agent");
;             asm volatile("s_waitcnt vmcnt(0)" ::: "memory");
;             const unsigned og = xb_add(&bar[XB_TOP], 1u);
;             const unsigned tg = og / nx;
;             if (og + 1u == (tg + 1u) * nx) xb_add(&bar[XB_TOPGEN], 1u);
;             else XB_SPIN(xb_ld(&bar[XB_TOPGEN]) == tg, bar);
;             __builtin_amdgcn_fence(__ATOMIC_ACQUIRE, "agent");
;             xb_add(&bar[XB_XGEN(b.x)], 1u);
;             asm volatile("s_waitcnt vmcnt(0)" ::: "memory");
;         } else {
;             XB_SPIN(xb_ld(&bar[XB_XGEN(b.x)]) == gen, bar);
.LBB0_3672:
	s_or_b64 exec, exec, s[38:39]
	v_cvt_f32_u32_e32 v4, v2
	s_waitcnt vmcnt(0)
	v_readfirstlane_b32 s7, v3
	v_sub_u32_e32 v3, 0, v2
	v_rcp_iflag_f32_e32 v4, v4
	v_add_u32_e32 v5, s7, v1
	v_mul_f32_e32 v4, 0x4f7ffffe, v4
	v_cvt_u32_f32_e32 v4, v4
	v_mul_lo_u32 v1, v3, v4
	v_mul_hi_u32 v1, v4, v1
	v_add_u32_e32 v1, v4, v1
	v_mul_hi_u32 v1, v5, v1
	v_mul_lo_u32 v3, v1, v2
	v_sub_u32_e32 v3, v5, v3
	v_add_u32_e32 v4, 1, v1
	v_cmp_ge_u32_e32 vcc, v3, v2
	s_nop 1
	v_cndmask_b32_e32 v1, v1, v4, vcc
	v_sub_u32_e32 v4, v3, v2
	v_cndmask_b32_e32 v3, v3, v4, vcc
	v_add_u32_e32 v4, 1, v1
	v_cmp_ge_u32_e32 vcc, v3, v2
	v_add_u32_e32 v3, 1, v5
	s_nop 0
	v_cndmask_b32_e32 v1, v1, v4, vcc
	v_mul_lo_u32 v4, v2, v1
	v_add_u32_e32 v2, v4, v2
	v_cmp_ne_u32_e32 vcc, v3, v2
	s_and_saveexec_b64 s[22:23], vcc
	s_xor_b64 s[38:39], exec, s[22:23]
	s_cbranch_execz .LBB0_3686
	v_readlane_b32 s22, v252, 57
	v_readlane_b32 s23, v252, 58
	s_waitcnt lgkmcnt(0)
	s_nop 3
	global_load_dword v0, v179, s[22:23] sc1
	s_waitcnt vmcnt(0)
	v_cmp_eq_u32_e32 vcc, v0, v1
	s_and_saveexec_b64 s[40:41], vcc
	s_cbranch_execz .LBB0_3685
	s_mov_b32 s7, 1
	s_mov_b64 s[42:43], 0
	s_branch .LBB0_3676

; __device__ __forceinline__ unsigned xb_ld(unsigned* p)              { return __hip_atomic_load(p, __ATOMIC_RELAXED, __HIP_MEMORY_SCOPE_AGENT); }
; #define XB_SPIN(cond, bar) do { unsigned _sp = 0; while (cond) { __builtin_amdgcn_s_sleep(1); \
;     if ((++_sp & 255u) == 0u) { if (xb_ld(&(bar)[XB_TMO])) break; if (_sp > XB_SPIN_CAP) { atomicAdd(&(bar)[XB_TMO], 1u); break; } } } } while (0)
; __device__ __forceinline__ void xcd_barrier(const XcdBarrier& b) {
;     ...
;             XB_SPIN(xb_ld(&bar[XB_XGEN(b.x)]) == gen, bar);
.LBB0_3678:
	v_readlane_b32 s22, v252, 57
	v_readlane_b32 s23, v252, 58
	s_add_i32 s7, s7, 1
	s_mov_b64 s[48:49], -1
	s_nop 2
	global_load_dword v0, v179, s[22:23] sc1
	s_waitcnt vmcnt(0)
	v_cmp_ne_u32_e32 vcc, v0, v1
	s_orn2_b64 s[46:47], vcc, exec
	s_branch .LBB0_3675

; __device__ __forceinline__ unsigned xb_ld(unsigned* p)              { return __hip_atomic_load(p, __ATOMIC_RELAXED, __HIP_MEMORY_SCOPE_AGENT); }
; __device__ __forceinline__ unsigned xb_add(unsigned* p, unsigned v) { return __hip_atomic_fetch_add(p, v, __ATOMIC_RELAXED, __HIP_MEMORY_SCOPE_AGENT); }
; #define XB_SPIN(cond, bar) do { unsigned _sp = 0; while (cond) { __builtin_amdgcn_s_sleep(1); \
;     if ((++_sp & 255u) == 0u) { if (xb_ld(&(bar)[XB_TMO])) break; if (_sp > XB_SPIN_CAP) { atomicAdd(&(bar)[XB_TMO], 1u); break; } } } } while (0)
; __device__ __forceinline__ void xcd_barrier(const XcdBarrier& b) {
;     ...
;         const unsigned old = xb_add(&bar[XB_XSUB(b.x)], 1u);
;         const unsigned gen = old / nloc;
;         if (old + 1u == (gen + 1u) * nloc) {
;             __builtin_amdgcn_fence(__ATOMIC_RELEASE, "agent");
;             asm volatile("s_waitcnt vmcnt(0)" ::: "memory");
;             const unsigned og = xb_add(&bar[XB_TOP], 1u);
;             const unsigned tg = og / nx;
;             if (og + 1u == (tg + 1u) * nx) xb_add(&bar[XB_TOPGEN], 1u);
;             else XB_SPIN(xb_ld(&bar[XB_TOPGEN]) == tg, bar);
;             __builtin_amdgcn_fence(__ATOMIC_ACQUIRE, "agent");
;             xb_add(&bar[XB_XGEN(b.x)], 1u);
;             asm volatile("s_waitcnt vmcnt(0)" ::: "memory");
;         } else {
;             XB_SPIN(xb_ld(&bar[XB_XGEN(b.x)]) == gen, bar);
.LBB0_3962:
	s_or_b64 exec, exec, s[2:3]
	v_cvt_f32_u32_e32 v4, v2
	s_waitcnt vmcnt(0)
	v_readfirstlane_b32 s2, v3
	v_sub_u32_e32 v3, 0, v2
	v_rcp_iflag_f32_e32 v4, v4
	v_add_u32_e32 v5, s2, v1
	v_mul_f32_e32 v4, 0x4f7ffffe, v4
	v_cvt_u32_f32_e32 v4, v4
	v_mul_lo_u32 v1, v3, v4
	v_mul_hi_u32 v1, v4, v1
	v_add_u32_e32 v1, v4, v1
	v_mul_hi_u32 v1, v5, v1
	v_mul_lo_u32 v3, v1, v2
	v_sub_u32_e32 v3, v5, v3
	v_add_u32_e32 v4, 1, v1
	v_cmp_ge_u32_e32 vcc, v3, v2
	s_nop 1
	v_cndmask_b32_e32 v1, v1, v4, vcc
	v_sub_u32_e32 v4, v3, v2
	v_cndmask_b32_e32 v3, v3, v4, vcc
	v_add_u32_e32 v4, 1, v1
	v_cmp_ge_u32_e32 vcc, v3, v2
	v_add_u32_e32 v3, 1, v5
	s_nop 0
	v_cndmask_b32_e32 v1, v1, v4, vcc
	v_mul_lo_u32 v4, v2, v1
	v_add_u32_e32 v2, v4, v2
	v_cmp_ne_u32_e32 vcc, v3, v2
	s_and_saveexec_b64 s[2:3], vcc
	s_xor_b64 s[2:3], exec, s[2:3]
	s_cbranch_execz .LBB0_3976
	v_readlane_b32 s6, v252, 57
	v_readlane_b32 s7, v252, 58
	s_waitcnt lgkmcnt(0)
	s_nop 3
	global_load_dword v0, v179, s[6:7] sc1
	s_waitcnt vmcnt(0)
	v_cmp_eq_u32_e32 vcc, v0, v1
	s_and_saveexec_b64 s[38:39], vcc
	s_cbranch_execz .LBB0_3975
	s_mov_b32 s4, 1
	s_mov_b64 s[40:41], 0
	s_branch .LBB0_3966

; __device__ __forceinline__ unsigned xb_ld(unsigned* p)              { return __hip_atomic_load(p, __ATOMIC_RELAXED, __HIP_MEMORY_SCOPE_AGENT); }
; #define XB_SPIN(cond, bar) do { unsigned _sp = 0; while (cond) { __builtin_amdgcn_s_sleep(1); \
;     if ((++_sp & 255u) == 0u) { if (xb_ld(&(bar)[XB_TMO])) break; if (_sp > XB_SPIN_CAP) { atomicAdd(&(bar)[XB_TMO], 1u); break; } } } } while (0)
; __device__ __forceinline__ void xcd_barrier(const XcdBarrier& b) {
;     ...
;             XB_SPIN(xb_ld(&bar[XB_XGEN(b.x)]) == gen, bar);
.LBB0_3968:
	v_readlane_b32 s6, v252, 57
	v_readlane_b32 s7, v252, 58
	s_add_i32 s4, s4, 1
	s_mov_b64 s[46:47], -1
	s_nop 2
	global_load_dword v0, v179, s[6:7] sc1
	s_waitcnt vmcnt(0)
	v_cmp_ne_u32_e32 vcc, v0, v1
	s_orn2_b64 s[44:45], vcc, exec
	s_branch .LBB0_3965
